# baseline (speedup 1.0000x reference)
; #define PG8_STAGE(bufoff, gbase, voff) do { _Pragma("unroll") for (int _i = 0; _i < 2; ++_i) \
;         __builtin_amdgcn_global_load_lds((const unsigned*)((const char*)(gbase) + (voff)[_i]), (PG8_LAS unsigned*)(lds + (bufoff) + ldsw + _i * 8192), 16, 0, 0); } while (0)
; #define PG8_LDA(dst, b, h) do { _Pragma("unroll") for (int m = 0; m < 4; ++m) _Pragma("unroll") for (int k = 0; k < 2; ++k) dst[m][k] = *(const PG8_LAS bf16x8*)(lds + PG8_SA(b, h) + aoff + m * 2048 + k * 1024); } while (0)
; #define PG8_LDB(dst, b, h) do { _Pragma("unroll") for (int n = 0; n < 2; ++n) _Pragma("unroll") for (int k = 0; k < 2; ++k) dst[n][k] = *(const PG8_LAS bf16x8*)(lds + PG8_SB(b, h) + boff + n * 2048 + k * 1024); } while (0)
; #define PG8_MMA(ai, bj, At, Bt) do { __builtin_amdgcn_s_setprio(1); _Pragma("unroll") for (int m = 0; m < 4; ++m) _Pragma("unroll") for (int n = 0; n < 2; ++n) _Pragma("unroll") for (int k = 0; k < 2; ++k) \
;         acc[ai][bj][m][n] = __builtin_amdgcn_mfma_f32_16x16x32_bf16(Bt[n][k], At[m][k], acc[ai][bj][m][n], 0, 0, 0); __builtin_amdgcn_s_setprio(0); } while (0)
; #define PG8_WAIT_V(n) asm volatile("s_waitcnt vmcnt(" #n ")" ::: "memory")
; #define PG8_WAIT_L(n) asm volatile("s_waitcnt lgkmcnt(" #n ")" ::: "memory")
; template <class Epi, class Sched, bool ALIGN_EPI = false, bool SP2 = false, bool AROWS128 = false>
; __device__ __forceinline__ void gemm_phase(PG8_LAS unsigned char* lds, const Gemm g, const Sched& S, const Epi& E) {
;     ...
;         const bool has_next = S.next(ui + 1, nxt);
;         const char* nA = has_next ? (const char*)g.A + (size_t)nxt.pm * tstep : cA; const char* nB = has_next ? (const char*)g.Bt + (size_t)nxt.pn * tstep : cB;
;         for (int t = 0; t < nt; t += 2) {
;             const bool last = (t == nt - 2);
;             const char* a1 = cA + (size_t)(t + 1) * kstep;
;             const char* a2 = last ? nA : cA + (size_t)(t + 2) * kstep; const char* b2 = last ? nB : cB + (size_t)(t + 2) * kstep;
;             const char* a3 = a2 + kstep; const char* b3 = b2 + kstep;
;             if (last && has_next) S.a_ready(nxt);
;             if constexpr (SP2) {
;             PG8_LDB(B0, 0, 0); PG8_LDB(B1, 0, 1); PG8_SCHED; PG8_LDA(At, 0, 0); PG8_STAGE(PG8_SA(1, 1), a1 + hstepA, voffA);
;             PG8_WAIT_V(8); PG8_WAIT_L(0); PG8_BAR; PG8_MMA(0, 0, At, B0); PG8_MMA(0, 1, At, B1); PG8_BAR; PG8_SCHED;
.LBB0_118:
	s_ashr_i32 s25, s24, 31
	s_lshl_b64 s[26:27], s[24:25], 19
	s_add_u32 s26, s46, s26
	s_addc_u32 s27, s47, s27
	s_and_b64 s[28:29], s[0:1], exec
	s_cselect_b32 s25, s27, s49
	s_cselect_b32 s76, s26, s48
	s_ashr_i32 s15, s14, 31
	s_lshl_b64 s[28:29], s[14:15], 19
	s_add_u32 s28, s82, s28
	s_addc_u32 s29, s83, s29
	s_and_b64 s[58:59], s[0:1], exec
	s_cselect_b32 s15, s29, s51
	s_cselect_b32 s77, s28, s50
	s_add_u32 s48, s48, 0x40080
	s_addc_u32 s49, s49, 0
	s_add_u32 s91, s50, 0x100
	v_mov_b32_e32 v0, 0
	s_addc_u32 s92, s51, 0
	s_mov_b32 s93, -2
	v_mov_b64_e32 v[0:1], 0
	v_mov_b64_e32 v[2:3], 0
	v_mov_b64_e32 v[4:5], 0
	v_mov_b64_e32 v[6:7], 0
	v_mov_b64_e32 v[8:9], 0
	v_mov_b64_e32 v[10:11], 0
	v_mov_b64_e32 v[12:13], 0
	v_mov_b64_e32 v[14:15], 0
	v_mov_b64_e32 v[16:17], 0
	v_mov_b64_e32 v[18:19], 0
	v_mov_b64_e32 v[20:21], 0
	v_mov_b64_e32 v[22:23], 0
	v_mov_b64_e32 v[24:25], 0
	v_mov_b64_e32 v[26:27], 0
	v_mov_b64_e32 v[28:29], 0
	v_mov_b64_e32 v[30:31], 0
	v_mov_b64_e32 v[32:33], 0
	v_mov_b64_e32 v[34:35], 0
	v_mov_b64_e32 v[36:37], 0
	v_mov_b64_e32 v[38:39], 0
	v_mov_b64_e32 v[40:41], 0
	v_mov_b64_e32 v[42:43], 0
	v_mov_b64_e32 v[44:45], 0
	v_mov_b64_e32 v[46:47], 0
	v_mov_b64_e32 v[48:49], 0
	v_mov_b64_e32 v[50:51], 0
	v_mov_b64_e32 v[52:53], 0
	v_mov_b64_e32 v[54:55], 0
	v_mov_b64_e32 v[56:57], 0
	v_mov_b64_e32 v[58:59], 0
	v_mov_b64_e32 v[60:61], 0
	v_mov_b64_e32 v[62:63], 0
	v_mov_b64_e32 v[64:65], 0
	v_mov_b64_e32 v[66:67], 0
	v_mov_b64_e32 v[68:69], 0
	v_mov_b64_e32 v[70:71], 0
	v_mov_b64_e32 v[72:73], 0
	v_mov_b64_e32 v[74:75], 0
	v_mov_b64_e32 v[76:77], 0
	v_mov_b64_e32 v[78:79], 0
	v_mov_b64_e32 v[80:81], 0
	v_mov_b64_e32 v[82:83], 0
	v_mov_b64_e32 v[84:85], 0
	v_mov_b64_e32 v[86:87], 0
	v_mov_b64_e32 v[88:89], 0
	v_mov_b64_e32 v[90:91], 0
	v_mov_b64_e32 v[92:93], 0
	v_mov_b64_e32 v[94:95], 0
	v_mov_b64_e32 v[96:97], 0
	v_mov_b64_e32 v[98:99], 0
	v_mov_b64_e32 v[100:101], 0
	v_mov_b64_e32 v[102:103], 0
	v_mov_b64_e32 v[104:105], 0
	v_mov_b64_e32 v[106:107], 0
	v_mov_b64_e32 v[108:109], 0
	v_mov_b64_e32 v[110:111], 0
	v_mov_b64_e32 v[112:113], 0
	v_mov_b64_e32 v[114:115], 0
	v_mov_b64_e32 v[116:117], 0
	v_mov_b64_e32 v[118:119], 0
	v_mov_b64_e32 v[120:121], 0
	v_mov_b64_e32 v[122:123], 0
	v_mov_b64_e32 v[124:125], 0
	v_mov_b64_e32 v[126:127], 0
	s_branch .LBB0_119
.Lrot_k0:
	s_barrier
.LBB0_119:
	ds_read_b128 v[148:151], v155
	ds_read_b128 v[160:163], v155 offset:1024
	ds_read_b128 v[164:167], v155 offset:2048
	ds_read_b128 v[168:171], v155 offset:3072
	ds_read_b128 v[172:175], v156
	ds_read_b128 v[176:179], v156 offset:1024
	ds_read_b128 v[180:183], v156 offset:2048
	ds_read_b128 v[184:187], v156 offset:3072
	s_add_u32 s50, s48, 0xfffc0080
	s_addc_u32 s51, s49, -1
	s_cmp_eq_u32 s93, 12
	s_cselect_b32 s59, s25, s51
	s_cselect_b32 s58, s76, s50
	s_cselect_b32 s51, s15, s92
	s_cselect_b32 s50, s77, s91
	v_lshl_add_u64 v[208:209], s[48:49], 0, v[138:139]
	s_add_i32 m0, s31, 0xc000
	ds_read_b128 v[188:191], v157
	ds_read_b128 v[192:195], v157 offset:1024
	ds_read_b128 v[196:199], v157 offset:2048
	ds_read_b128 v[200:203], v157 offset:3072
	ds_read_b128 v[204:207], v157 offset:4096
	ds_read_b128 v[212:215], v157 offset:5120
	ds_read_b128 v[216:219], v157 offset:6144
	ds_read_b128 v[220:223], v157 offset:7168
	global_load_lds_dwordx4 v[208:209], off
	v_lshl_add_u64 v[208:209], s[48:49], 0, v[140:141]
	s_add_i32 m0, s31, 0xe000
	s_nop 0
	global_load_lds_dwordx4 v[208:209], off
	s_waitcnt vmcnt(8)
	s_waitcnt lgkmcnt(0)
	s_barrier
	s_setprio 1
	s_waitcnt lgkmcnt(0)
	v_mfma_f32_16x16x32_bf16 v[124:127], v[148:151], v[188:191], v[124:127]
	v_mfma_f32_16x16x32_bf16 v[120:123], v[164:167], v[188:191], v[120:123]
	v_mfma_f32_16x16x32_bf16 v[112:115], v[148:151], v[196:199], v[112:115]
	v_mfma_f32_16x16x32_bf16 v[104:107], v[164:167], v[196:199], v[104:107]
	v_mfma_f32_16x16x32_bf16 v[96:99], v[148:151], v[204:207], v[96:99]
	v_mfma_f32_16x16x32_bf16 v[88:91], v[164:167], v[204:207], v[88:91]
	v_mfma_f32_16x16x32_bf16 v[80:83], v[148:151], v[216:219], v[80:83]
	v_mfma_f32_16x16x32_bf16 v[72:75], v[164:167], v[216:219], v[72:75]
	v_mfma_f32_16x16x32_bf16 v[124:127], v[160:163], v[192:195], v[124:127]
	v_mfma_f32_16x16x32_bf16 v[120:123], v[168:171], v[192:195], v[120:123]
	v_mfma_f32_16x16x32_bf16 v[112:115], v[160:163], v[200:203], v[112:115]
	v_mfma_f32_16x16x32_bf16 v[104:107], v[168:171], v[200:203], v[104:107]
	v_mfma_f32_16x16x32_bf16 v[96:99], v[160:163], v[212:215], v[96:99]
	v_mfma_f32_16x16x32_bf16 v[88:91], v[168:171], v[212:215], v[88:91]
	v_mfma_f32_16x16x32_bf16 v[80:83], v[160:163], v[220:223], v[80:83]
	v_mfma_f32_16x16x32_bf16 v[72:75], v[168:171], v[220:223], v[72:75]
	s_setprio 0
	s_setprio 1
	v_mfma_f32_16x16x32_bf16 v[116:119], v[172:175], v[188:191], v[116:119]
	v_mfma_f32_16x16x32_bf16 v[108:111], v[180:183], v[188:191], v[108:111]
	v_mfma_f32_16x16x32_bf16 v[100:103], v[172:175], v[196:199], v[100:103]
	v_mfma_f32_16x16x32_bf16 v[92:95], v[180:183], v[196:199], v[92:95]
	v_mfma_f32_16x16x32_bf16 v[84:87], v[172:175], v[204:207], v[84:87]
	v_mfma_f32_16x16x32_bf16 v[76:79], v[180:183], v[204:207], v[76:79]
	v_mfma_f32_16x16x32_bf16 v[68:71], v[172:175], v[216:219], v[68:71]
	v_mfma_f32_16x16x32_bf16 v[64:67], v[180:183], v[216:219], v[64:67]
	v_mfma_f32_16x16x32_bf16 v[116:119], v[176:179], v[192:195], v[116:119]
	v_mfma_f32_16x16x32_bf16 v[108:111], v[184:187], v[192:195], v[108:111]
	v_mfma_f32_16x16x32_bf16 v[100:103], v[176:179], v[200:203], v[100:103]
	v_mfma_f32_16x16x32_bf16 v[92:95], v[184:187], v[200:203], v[92:95]
	v_mfma_f32_16x16x32_bf16 v[84:87], v[176:179], v[212:215], v[84:87]
	v_mfma_f32_16x16x32_bf16 v[76:79], v[184:187], v[212:215], v[76:79]
	v_mfma_f32_16x16x32_bf16 v[68:71], v[176:179], v[220:223], v[68:71]
	v_mfma_f32_16x16x32_bf16 v[64:67], v[184:187], v[220:223], v[64:67]
	s_setprio 0
	s_barrier
; #define PG8_STAGE(bufoff, gbase, voff) do { _Pragma("unroll") for (int _i = 0; _i < 2; ++_i) \
;         __builtin_amdgcn_global_load_lds((const unsigned*)((const char*)(gbase) + (voff)[_i]), (PG8_LAS unsigned*)(lds + (bufoff) + ldsw + _i * 8192), 16, 0, 0); } while (0)
; #define PG8_LDA(dst, b, h) do { _Pragma("unroll") for (int m = 0; m < 4; ++m) _Pragma("unroll") for (int k = 0; k < 2; ++k) dst[m][k] = *(const PG8_LAS bf16x8*)(lds + PG8_SA(b, h) + aoff + m * 2048 + k * 1024); } while (0)
; #define PG8_LDB(dst, b, h) do { _Pragma("unroll") for (int n = 0; n < 2; ++n) _Pragma("unroll") for (int k = 0; k < 2; ++k) dst[n][k] = *(const PG8_LAS bf16x8*)(lds + PG8_SB(b, h) + boff + n * 2048 + k * 1024); } while (0)
; #define PG8_MMA(ai, bj, At, Bt) do { __builtin_amdgcn_s_setprio(1); _Pragma("unroll") for (int m = 0; m < 4; ++m) _Pragma("unroll") for (int n = 0; n < 2; ++n) _Pragma("unroll") for (int k = 0; k < 2; ++k) \
;         acc[ai][bj][m][n] = __builtin_amdgcn_mfma_f32_16x16x32_bf16(Bt[n][k], At[m][k], acc[ai][bj][m][n], 0, 0, 0); __builtin_amdgcn_s_setprio(0); } while (0)
; #define PG8_WAIT_V(n) asm volatile("s_waitcnt vmcnt(" #n ")" ::: "memory")
; #define PG8_WAIT_L(n) asm volatile("s_waitcnt lgkmcnt(" #n ")" ::: "memory")
; #define PG8_BAR __builtin_amdgcn_s_barrier()
; #define PG8_SCHED __builtin_amdgcn_sched_barrier(0)
; template <class Epi, class Sched, bool ALIGN_EPI = false, bool SP2 = false, bool AROWS128 = false>
; __device__ __forceinline__ void gemm_phase(PG8_LAS unsigned char* lds, const Gemm g, const Sched& S, const Epi& E) {
;     ...
;             PG8_LDA(At, 0, 1); PG8_STAGE(PG8_SB(0, 0), b2, voffB); PG8_STAGE(PG8_SB(0, 1), b2 + hstep, voffB); PG8_STAGE(PG8_SA(0, 0), a2, voffA);
;             PG8_WAIT_V(8); PG8_WAIT_L(0); PG8_BAR; PG8_MMA(1, 0, At, B0); PG8_MMA(1, 1, At, B1); PG8_BAR; PG8_SCHED;
;             PG8_LDB(B0, 1, 0); PG8_LDB(B1, 1, 1); PG8_SCHED; PG8_LDA(At, 1, 0); PG8_STAGE(PG8_SA(0, 1), a2 + hstepA, voffA);
;             PG8_WAIT_V(8); PG8_WAIT_L(0); PG8_BAR; PG8_MMA(0, 0, At, B0); PG8_MMA(0, 1, At, B1); PG8_BAR; PG8_SCHED;
	s_add_i32 s94, s87, s3
	v_lshl_add_u64 v[208:209], s[50:51], 0, v[134:135]
	s_mov_b32 m0, s94
	ds_read_b128 v[188:191], v157 offset:16384
	ds_read_b128 v[192:195], v157 offset:17408
	ds_read_b128 v[196:199], v157 offset:18432
	ds_read_b128 v[200:203], v157 offset:19456
	ds_read_b128 v[204:207], v157 offset:20480
	ds_read_b128 v[212:215], v157 offset:21504
	ds_read_b128 v[216:219], v157 offset:22528
	ds_read_b128 v[220:223], v157 offset:23552
	global_load_lds_dwordx4 v[208:209], off
	s_add_i32 m0, s94, 0x2000
	s_add_u32 s94, s50, 0x40000
	v_lshl_add_u64 v[224:225], s[50:51], 0, v[130:131]
	s_addc_u32 s95, s51, 0
	s_add_i32 s96, s88, s3
	global_load_lds_dwordx4 v[224:225], off
	v_lshl_add_u64 v[226:227], s[94:95], 0, v[134:135]
	s_mov_b32 m0, s96
	v_lshl_add_u64 v[228:229], s[58:59], 0, v[132:133]
	global_load_lds_dwordx4 v[226:227], off
	v_lshl_add_u64 v[226:227], s[94:95], 0, v[130:131]
	s_add_i32 m0, s96, 0x2000
	s_nop 0
	global_load_lds_dwordx4 v[226:227], off
	v_lshl_add_u64 v[226:227], s[58:59], 0, v[136:137]
	s_mov_b32 m0, s31
	s_nop 0
	global_load_lds_dwordx4 v[226:227], off
	s_mov_b32 m0, s64
	s_nop 0
	global_load_lds_dwordx4 v[228:229], off
	s_waitcnt vmcnt(8)
	s_waitcnt lgkmcnt(0)
	s_barrier
	s_setprio 1
	s_waitcnt lgkmcnt(0)
	v_mfma_f32_16x16x32_bf16 v[60:63], v[148:151], v[188:191], v[60:63]
	v_mfma_f32_16x16x32_bf16 v[56:59], v[164:167], v[188:191], v[56:59]
	v_mfma_f32_16x16x32_bf16 v[48:51], v[148:151], v[196:199], v[48:51]
	v_mfma_f32_16x16x32_bf16 v[40:43], v[164:167], v[196:199], v[40:43]
	v_mfma_f32_16x16x32_bf16 v[32:35], v[148:151], v[204:207], v[32:35]
	v_mfma_f32_16x16x32_bf16 v[24:27], v[164:167], v[204:207], v[24:27]
	v_mfma_f32_16x16x32_bf16 v[16:19], v[148:151], v[216:219], v[16:19]
	v_mfma_f32_16x16x32_bf16 v[8:11], v[164:167], v[216:219], v[8:11]
	v_mfma_f32_16x16x32_bf16 v[60:63], v[160:163], v[192:195], v[60:63]
	v_mfma_f32_16x16x32_bf16 v[56:59], v[168:171], v[192:195], v[56:59]
	v_mfma_f32_16x16x32_bf16 v[48:51], v[160:163], v[200:203], v[48:51]
	v_mfma_f32_16x16x32_bf16 v[40:43], v[168:171], v[200:203], v[40:43]
	v_mfma_f32_16x16x32_bf16 v[32:35], v[160:163], v[212:215], v[32:35]
	v_mfma_f32_16x16x32_bf16 v[24:27], v[168:171], v[212:215], v[24:27]
	v_mfma_f32_16x16x32_bf16 v[16:19], v[160:163], v[220:223], v[16:19]
	v_mfma_f32_16x16x32_bf16 v[8:11], v[168:171], v[220:223], v[8:11]
	s_setprio 0
	s_setprio 1
	v_mfma_f32_16x16x32_bf16 v[52:55], v[172:175], v[188:191], v[52:55]
	v_mfma_f32_16x16x32_bf16 v[44:47], v[180:183], v[188:191], v[44:47]
	v_mfma_f32_16x16x32_bf16 v[36:39], v[172:175], v[196:199], v[36:39]
	v_mfma_f32_16x16x32_bf16 v[28:31], v[180:183], v[196:199], v[28:31]
	v_mfma_f32_16x16x32_bf16 v[20:23], v[172:175], v[204:207], v[20:23]
	v_mfma_f32_16x16x32_bf16 v[12:15], v[180:183], v[204:207], v[12:15]
	v_mfma_f32_16x16x32_bf16 v[4:7], v[172:175], v[216:219], v[4:7]
	v_mfma_f32_16x16x32_bf16 v[0:3], v[180:183], v[216:219], v[0:3]
	v_mfma_f32_16x16x32_bf16 v[52:55], v[176:179], v[192:195], v[52:55]
	v_mfma_f32_16x16x32_bf16 v[44:47], v[184:187], v[192:195], v[44:47]
	v_mfma_f32_16x16x32_bf16 v[36:39], v[176:179], v[200:203], v[36:39]
	v_mfma_f32_16x16x32_bf16 v[28:31], v[184:187], v[200:203], v[28:31]
	v_mfma_f32_16x16x32_bf16 v[20:23], v[176:179], v[212:215], v[20:23]
	v_mfma_f32_16x16x32_bf16 v[12:15], v[184:187], v[212:215], v[12:15]
	v_mfma_f32_16x16x32_bf16 v[4:7], v[176:179], v[220:223], v[4:7]
	v_mfma_f32_16x16x32_bf16 v[0:3], v[184:187], v[220:223], v[0:3]
	s_setprio 0
	s_barrier
	s_add_i32 s94, 0, 0x18000
	v_add_u32_e32 v146, s94, v153
	s_add_i32 s95, 0, 0x1c000
	ds_read_b128 v[148:151], v146
	ds_read_b128 v[160:163], v146 offset:1024
	ds_read_b128 v[164:167], v146 offset:2048
	ds_read_b128 v[168:171], v146 offset:3072
	v_add_u32_e32 v146, s95, v153
	ds_read_b128 v[172:175], v146
	ds_read_b128 v[176:179], v146 offset:1024
	ds_read_b128 v[180:183], v146 offset:2048
	ds_read_b128 v[184:187], v146 offset:3072
	s_add_u32 s58, s58, 0x40000
	s_addc_u32 s59, s59, 0
	s_mov_b32 m0, s65
	v_lshl_add_u64 v[230:231], s[58:59], 0, v[136:137]
	ds_read_b128 v[188:191], v157 offset:32768
	ds_read_b128 v[192:195], v157 offset:33792
	ds_read_b128 v[196:199], v157 offset:34816
	ds_read_b128 v[200:203], v157 offset:35840
	ds_read_b128 v[204:207], v157 offset:36864
	ds_read_b128 v[212:215], v157 offset:37888
	ds_read_b128 v[216:219], v157 offset:38912
	ds_read_b128 v[220:223], v157 offset:39936
	global_load_lds_dwordx4 v[230:231], off
	v_lshl_add_u64 v[230:231], s[58:59], 0, v[132:133]
	s_mov_b32 m0, s72
	s_nop 0
	global_load_lds_dwordx4 v[230:231], off
	s_waitcnt vmcnt(8)
	s_waitcnt lgkmcnt(0)
	s_barrier
; #define PG8_STAGE(bufoff, gbase, voff) do { _Pragma("unroll") for (int _i = 0; _i < 2; ++_i) \
;         __builtin_amdgcn_global_load_lds((const unsigned*)((const char*)(gbase) + (voff)[_i]), (PG8_LAS unsigned*)(lds + (bufoff) + ldsw + _i * 8192), 16, 0, 0); } while (0)
; #define PG8_LDA(dst, b, h) do { _Pragma("unroll") for (int m = 0; m < 4; ++m) _Pragma("unroll") for (int k = 0; k < 2; ++k) dst[m][k] = *(const PG8_LAS bf16x8*)(lds + PG8_SA(b, h) + aoff + m * 2048 + k * 1024); } while (0)
; #define PG8_MMA(ai, bj, At, Bt) do { __builtin_amdgcn_s_setprio(1); _Pragma("unroll") for (int m = 0; m < 4; ++m) _Pragma("unroll") for (int n = 0; n < 2; ++n) _Pragma("unroll") for (int k = 0; k < 2; ++k) \
;         acc[ai][bj][m][n] = __builtin_amdgcn_mfma_f32_16x16x32_bf16(Bt[n][k], At[m][k], acc[ai][bj][m][n], 0, 0, 0); __builtin_amdgcn_s_setprio(0); } while (0)
; #define PG8_WAIT_V(n) asm volatile("s_waitcnt vmcnt(" #n ")" ::: "memory")
; #define PG8_WAIT_L(n) asm volatile("s_waitcnt lgkmcnt(" #n ")" ::: "memory")
; #define PG8_BAR __builtin_amdgcn_s_barrier()
; #define PG8_SCHED __builtin_amdgcn_sched_barrier(0)
; template <class Epi, class Sched, bool ALIGN_EPI = false, bool SP2 = false, bool AROWS128 = false>
; __device__ __forceinline__ void gemm_phase(PG8_LAS unsigned char* lds, const Gemm g, const Sched& S, const Epi& E) {
;     ...
;         for (int t = 0; t < nt; t += 2) {
;     ...
;             PG8_WAIT_V(8); PG8_WAIT_L(0); PG8_BAR; PG8_MMA(0, 0, At, B0); PG8_MMA(0, 1, At, B1); PG8_BAR; PG8_SCHED;
;             PG8_LDA(At, 1, 1); PG8_STAGE(PG8_SB(1, 0), b3, voffB); PG8_STAGE(PG8_SB(1, 1), b3 + hstep, voffB); PG8_STAGE(PG8_SA(1, 0), a3, voffA);
;             PG8_WAIT_V(8); PG8_WAIT_L(0); PG8_BAR; PG8_MMA(1, 0, At, B0); PG8_MMA(1, 1, At, B1); PG8_BAR; PG8_SCHED;
	s_setprio 1
	s_waitcnt lgkmcnt(0)
	v_mfma_f32_16x16x32_bf16 v[124:127], v[148:151], v[188:191], v[124:127]
	v_mfma_f32_16x16x32_bf16 v[120:123], v[164:167], v[188:191], v[120:123]
	v_mfma_f32_16x16x32_bf16 v[112:115], v[148:151], v[196:199], v[112:115]
	v_mfma_f32_16x16x32_bf16 v[104:107], v[164:167], v[196:199], v[104:107]
	v_mfma_f32_16x16x32_bf16 v[96:99], v[148:151], v[204:207], v[96:99]
	v_mfma_f32_16x16x32_bf16 v[88:91], v[164:167], v[204:207], v[88:91]
	v_mfma_f32_16x16x32_bf16 v[80:83], v[148:151], v[216:219], v[80:83]
	v_mfma_f32_16x16x32_bf16 v[72:75], v[164:167], v[216:219], v[72:75]
	v_mfma_f32_16x16x32_bf16 v[124:127], v[160:163], v[192:195], v[124:127]
	v_mfma_f32_16x16x32_bf16 v[120:123], v[168:171], v[192:195], v[120:123]
	v_mfma_f32_16x16x32_bf16 v[112:115], v[160:163], v[200:203], v[112:115]
	v_mfma_f32_16x16x32_bf16 v[104:107], v[168:171], v[200:203], v[104:107]
	v_mfma_f32_16x16x32_bf16 v[96:99], v[160:163], v[212:215], v[96:99]
	v_mfma_f32_16x16x32_bf16 v[88:91], v[168:171], v[212:215], v[88:91]
	v_mfma_f32_16x16x32_bf16 v[80:83], v[160:163], v[220:223], v[80:83]
	v_mfma_f32_16x16x32_bf16 v[72:75], v[168:171], v[220:223], v[72:75]
	s_setprio 0
	s_setprio 1
	v_mfma_f32_16x16x32_bf16 v[116:119], v[172:175], v[188:191], v[116:119]
	v_mfma_f32_16x16x32_bf16 v[108:111], v[180:183], v[188:191], v[108:111]
	v_mfma_f32_16x16x32_bf16 v[100:103], v[172:175], v[196:199], v[100:103]
	v_mfma_f32_16x16x32_bf16 v[92:95], v[180:183], v[196:199], v[92:95]
	v_mfma_f32_16x16x32_bf16 v[84:87], v[172:175], v[204:207], v[84:87]
	v_mfma_f32_16x16x32_bf16 v[76:79], v[180:183], v[204:207], v[76:79]
	v_mfma_f32_16x16x32_bf16 v[68:71], v[172:175], v[216:219], v[68:71]
	v_mfma_f32_16x16x32_bf16 v[64:67], v[180:183], v[216:219], v[64:67]
	v_mfma_f32_16x16x32_bf16 v[116:119], v[176:179], v[192:195], v[116:119]
	v_mfma_f32_16x16x32_bf16 v[108:111], v[184:187], v[192:195], v[108:111]
	v_mfma_f32_16x16x32_bf16 v[100:103], v[176:179], v[200:203], v[100:103]
	v_mfma_f32_16x16x32_bf16 v[92:95], v[184:187], v[200:203], v[92:95]
	v_mfma_f32_16x16x32_bf16 v[84:87], v[176:179], v[212:215], v[84:87]
	v_mfma_f32_16x16x32_bf16 v[76:79], v[184:187], v[212:215], v[76:79]
	v_mfma_f32_16x16x32_bf16 v[68:71], v[176:179], v[220:223], v[68:71]
	v_mfma_f32_16x16x32_bf16 v[64:67], v[184:187], v[220:223], v[64:67]
	s_setprio 0
	s_barrier
	s_add_i32 s58, s94, s3
	v_lshl_add_u64 v[208:209], v[208:209], 0, s[6:7]
	s_mov_b32 m0, s58
	ds_read_b128 v[188:191], v157 offset:49152
	ds_read_b128 v[192:195], v157 offset:50176
	ds_read_b128 v[196:199], v157 offset:51200
	ds_read_b128 v[200:203], v157 offset:52224
	ds_read_b128 v[204:207], v157 offset:53248
	ds_read_b128 v[212:215], v157 offset:54272
	ds_read_b128 v[216:219], v157 offset:55296
	ds_read_b128 v[220:223], v157 offset:56320
	global_load_lds_dwordx4 v[208:209], off
	s_add_i32 m0, s58, 0x2000
	s_add_u32 s50, s50, 0x40080
	v_lshl_add_u64 v[208:209], v[224:225], 0, s[6:7]
	s_addc_u32 s51, s51, 0
	s_add_i32 s58, s95, s3
	global_load_lds_dwordx4 v[208:209], off
	v_lshl_add_u64 v[208:209], s[50:51], 0, v[134:135]
	s_mov_b32 m0, s58
	s_nop 0
	global_load_lds_dwordx4 v[208:209], off
	v_lshl_add_u64 v[208:209], s[50:51], 0, v[130:131]
	s_add_i32 m0, s58, 0x2000
	s_nop 0
	global_load_lds_dwordx4 v[208:209], off
	v_lshl_add_u64 v[208:209], v[226:227], 0, s[6:7]
	s_mov_b32 m0, s81
	s_nop 0
	global_load_lds_dwordx4 v[208:209], off
	v_lshl_add_u64 v[208:209], v[228:229], 0, s[6:7]
	s_mov_b32 m0, s84
	s_nop 0
	global_load_lds_dwordx4 v[208:209], off
	s_waitcnt vmcnt(8)
	s_waitcnt lgkmcnt(0)
	s_barrier
	s_setprio 1
	s_waitcnt lgkmcnt(0)
	v_mfma_f32_16x16x32_bf16 v[60:63], v[148:151], v[188:191], v[60:63]
	v_mfma_f32_16x16x32_bf16 v[56:59], v[164:167], v[188:191], v[56:59]
	v_mfma_f32_16x16x32_bf16 v[48:51], v[148:151], v[196:199], v[48:51]
	v_mfma_f32_16x16x32_bf16 v[40:43], v[164:167], v[196:199], v[40:43]
	v_mfma_f32_16x16x32_bf16 v[32:35], v[148:151], v[204:207], v[32:35]
	v_mfma_f32_16x16x32_bf16 v[24:27], v[164:167], v[204:207], v[24:27]
	v_mfma_f32_16x16x32_bf16 v[16:19], v[148:151], v[216:219], v[16:19]
	v_mfma_f32_16x16x32_bf16 v[8:11], v[164:167], v[216:219], v[8:11]
	v_mfma_f32_16x16x32_bf16 v[60:63], v[160:163], v[192:195], v[60:63]
	v_mfma_f32_16x16x32_bf16 v[56:59], v[168:171], v[192:195], v[56:59]
	v_mfma_f32_16x16x32_bf16 v[48:51], v[160:163], v[200:203], v[48:51]
	v_mfma_f32_16x16x32_bf16 v[40:43], v[168:171], v[200:203], v[40:43]
	v_mfma_f32_16x16x32_bf16 v[32:35], v[160:163], v[212:215], v[32:35]
	v_mfma_f32_16x16x32_bf16 v[24:27], v[168:171], v[212:215], v[24:27]
	v_mfma_f32_16x16x32_bf16 v[16:19], v[160:163], v[220:223], v[16:19]
	v_mfma_f32_16x16x32_bf16 v[8:11], v[168:171], v[220:223], v[8:11]
	s_setprio 0
	s_setprio 1
	v_mfma_f32_16x16x32_bf16 v[52:55], v[172:175], v[188:191], v[52:55]
	v_mfma_f32_16x16x32_bf16 v[44:47], v[180:183], v[188:191], v[44:47]
	v_mfma_f32_16x16x32_bf16 v[36:39], v[172:175], v[196:199], v[36:39]
	v_mfma_f32_16x16x32_bf16 v[28:31], v[180:183], v[196:199], v[28:31]
	v_mfma_f32_16x16x32_bf16 v[20:23], v[172:175], v[204:207], v[20:23]
	v_mfma_f32_16x16x32_bf16 v[12:15], v[180:183], v[204:207], v[12:15]
	v_mfma_f32_16x16x32_bf16 v[4:7], v[172:175], v[216:219], v[4:7]
	v_mfma_f32_16x16x32_bf16 v[0:3], v[180:183], v[216:219], v[0:3]
	v_mfma_f32_16x16x32_bf16 v[52:55], v[176:179], v[192:195], v[52:55]
	v_mfma_f32_16x16x32_bf16 v[44:47], v[184:187], v[192:195], v[44:47]
	v_mfma_f32_16x16x32_bf16 v[36:39], v[176:179], v[200:203], v[36:39]
	v_mfma_f32_16x16x32_bf16 v[28:31], v[184:187], v[200:203], v[28:31]
	v_mfma_f32_16x16x32_bf16 v[20:23], v[176:179], v[212:215], v[20:23]
	v_mfma_f32_16x16x32_bf16 v[12:15], v[184:187], v[212:215], v[12:15]
	v_mfma_f32_16x16x32_bf16 v[4:7], v[176:179], v[220:223], v[4:7]
	v_mfma_f32_16x16x32_bf16 v[0:3], v[184:187], v[220:223], v[0:3]
	s_setprio 0
	s_add_i32 s93, s93, 2
	s_add_u32 s48, s48, 0x100
	s_addc_u32 s49, s49, 0
	s_add_u32 s91, s91, 0x100
	s_addc_u32 s92, s92, 0
	s_cmp_gt_u32 s93, 13
	s_cbranch_scc0 .Lrot_k0
	s_barrier
	s_and_b64 vcc, exec, s[10:11]
	s_cbranch_vccz .LBB0_122
	s_barrier

; template <class Epi, class Sched, bool ALIGN_EPI = false, bool SP2 = false, bool AROWS128 = false>
; __device__ __forceinline__ void gemm_phase(PG8_LAS unsigned char* lds, const Gemm g, const Sched& S, const Epi& E) {
;     ...
;         const bool has_next = S.next(ui + 1, nxt);
;         const char* nA = has_next ? (const char*)g.A + (size_t)nxt.pm * tstep : cA; const char* nB = has_next ? (const char*)g.Bt + (size_t)nxt.pn * tstep : cB;
;     ...
; #pragma unroll
;         for (int a = 0; a < 2; ++a)
; #pragma unroll
;             for (int b = 0; b < 2; ++b)
; #pragma unroll
;                 for (int m = 0; m < 4; ++m)
; #pragma unroll
;                     for (int n = 0; n < 2; ++n) acc[a][b][m][n] = (f32x4){0.f, 0.f, 0.f, 0.f};
.LBB0_488:
	s_ashr_i32 s15, s14, 31
	s_lshl_b64 s[16:17], s[14:15], 19
	s_add_u32 s16, s46, s16
	s_addc_u32 s17, s47, s17
	s_and_b64 s[18:19], s[0:1], exec
	s_cselect_b32 s15, s17, s27
	s_cselect_b32 s76, s16, s26
	s_ashr_i32 s13, s12, 31
	s_lshl_b64 s[18:19], s[12:13], 19
	s_add_u32 s18, s20, s18
	s_addc_u32 s19, s21, s19
	s_and_b64 s[30:31], s[0:1], exec
	s_cselect_b32 s13, s19, s29
	s_cselect_b32 s77, s18, s28
	s_add_u32 s26, s26, 0x40080
	s_addc_u32 s27, s27, 0
	s_add_u32 s82, s28, 0x100
	v_mov_b32_e32 v0, 0
	s_addc_u32 s83, s29, 0
	s_mov_b32 s84, -2
	v_mov_b64_e32 v[0:1], 0
	v_mov_b64_e32 v[2:3], 0
	v_mov_b64_e32 v[4:5], 0
	v_mov_b64_e32 v[6:7], 0
	v_mov_b64_e32 v[8:9], 0
	v_mov_b64_e32 v[10:11], 0
	v_mov_b64_e32 v[12:13], 0
	v_mov_b64_e32 v[14:15], 0
	v_mov_b64_e32 v[16:17], 0
	v_mov_b64_e32 v[18:19], 0
	v_mov_b64_e32 v[20:21], 0
	v_mov_b64_e32 v[22:23], 0
	v_mov_b64_e32 v[24:25], 0
	v_mov_b64_e32 v[26:27], 0
	v_mov_b64_e32 v[28:29], 0
	v_mov_b64_e32 v[30:31], 0
	v_mov_b64_e32 v[32:33], 0
	v_mov_b64_e32 v[34:35], 0
	v_mov_b64_e32 v[36:37], 0
	v_mov_b64_e32 v[38:39], 0
	v_mov_b64_e32 v[40:41], 0
	v_mov_b64_e32 v[42:43], 0
	v_mov_b64_e32 v[44:45], 0
	v_mov_b64_e32 v[46:47], 0
	v_mov_b64_e32 v[48:49], 0
	v_mov_b64_e32 v[50:51], 0
	v_mov_b64_e32 v[52:53], 0
	v_mov_b64_e32 v[54:55], 0
	v_mov_b64_e32 v[56:57], 0
	v_mov_b64_e32 v[58:59], 0
	v_mov_b64_e32 v[60:61], 0
	v_mov_b64_e32 v[62:63], 0
	v_mov_b64_e32 v[64:65], 0
	v_mov_b64_e32 v[66:67], 0
	v_mov_b64_e32 v[68:69], 0
	v_mov_b64_e32 v[70:71], 0
	v_mov_b64_e32 v[72:73], 0
	v_mov_b64_e32 v[74:75], 0
	v_mov_b64_e32 v[76:77], 0
	v_mov_b64_e32 v[78:79], 0
	v_mov_b64_e32 v[80:81], 0
	v_mov_b64_e32 v[82:83], 0
	v_mov_b64_e32 v[84:85], 0
	v_mov_b64_e32 v[86:87], 0
	v_mov_b64_e32 v[88:89], 0
	v_mov_b64_e32 v[90:91], 0
	v_mov_b64_e32 v[92:93], 0
	v_mov_b64_e32 v[94:95], 0
	v_mov_b64_e32 v[96:97], 0
	v_mov_b64_e32 v[98:99], 0
	v_mov_b64_e32 v[100:101], 0
	v_mov_b64_e32 v[102:103], 0
	v_mov_b64_e32 v[104:105], 0
	v_mov_b64_e32 v[106:107], 0
	v_mov_b64_e32 v[108:109], 0
	v_mov_b64_e32 v[110:111], 0
	v_mov_b64_e32 v[112:113], 0
	v_mov_b64_e32 v[114:115], 0
	v_mov_b64_e32 v[116:117], 0
	v_mov_b64_e32 v[118:119], 0
	v_mov_b64_e32 v[120:121], 0
	v_mov_b64_e32 v[122:123], 0
	v_mov_b64_e32 v[124:125], 0
	v_mov_b64_e32 v[126:127], 0
	s_branch .LBB0_489

; #define PG8_STAGE(bufoff, gbase, voff) do { _Pragma("unroll") for (int _i = 0; _i < 2; ++_i) \
;         __builtin_amdgcn_global_load_lds((const unsigned*)((const char*)(gbase) + (voff)[_i]), (PG8_LAS unsigned*)(lds + (bufoff) + ldsw + _i * 8192), 16, 0, 0); } while (0)
; #define PG8_LDA(dst, b, h) do { _Pragma("unroll") for (int m = 0; m < 4; ++m) _Pragma("unroll") for (int k = 0; k < 2; ++k) dst[m][k] = *(const PG8_LAS bf16x8*)(lds + PG8_SA(b, h) + aoff + m * 2048 + k * 1024); } while (0)
; #define PG8_LDB(dst, b, h) do { _Pragma("unroll") for (int n = 0; n < 2; ++n) _Pragma("unroll") for (int k = 0; k < 2; ++k) dst[n][k] = *(const PG8_LAS bf16x8*)(lds + PG8_SB(b, h) + boff + n * 2048 + k * 1024); } while (0)
; #define PG8_MMA(ai, bj, At, Bt) do { __builtin_amdgcn_s_setprio(1); _Pragma("unroll") for (int m = 0; m < 4; ++m) _Pragma("unroll") for (int n = 0; n < 2; ++n) _Pragma("unroll") for (int k = 0; k < 2; ++k) \
;         acc[ai][bj][m][n] = __builtin_amdgcn_mfma_f32_16x16x32_bf16(Bt[n][k], At[m][k], acc[ai][bj][m][n], 0, 0, 0); __builtin_amdgcn_s_setprio(0); } while (0)
; #define PG8_WAIT_V(n) asm volatile("s_waitcnt vmcnt(" #n ")" ::: "memory")
; #define PG8_WAIT_L(n) asm volatile("s_waitcnt lgkmcnt(" #n ")" ::: "memory")
; #define PG8_BAR __builtin_amdgcn_s_barrier()
; #define PG8_SCHED __builtin_amdgcn_sched_barrier(0)
; template <class Epi, class Sched, bool ALIGN_EPI = false, bool SP2 = false, bool AROWS128 = false>
; __device__ __forceinline__ void gemm_phase(PG8_LAS unsigned char* lds, const Gemm g, const Sched& S, const Epi& E) {
;     ...
;             PG8_LDB(B0, 0, 0); PG8_LDB(B1, 0, 1); PG8_SCHED; PG8_LDA(At, 0, 0); PG8_STAGE(PG8_SA(1, 1), a1 + hstepA, voffA);
;             PG8_WAIT_V(8); PG8_WAIT_L(0); PG8_BAR; PG8_MMA(0, 0, At, B0); PG8_MMA(0, 1, At, B1); PG8_BAR; PG8_SCHED;
.LBB0_489:
	ds_read_b128 v[152:155], v149
	ds_read_b128 v[156:159], v149 offset:1024
	ds_read_b128 v[160:163], v149 offset:2048
	ds_read_b128 v[164:167], v149 offset:3072
	ds_read_b128 v[168:171], v150
	ds_read_b128 v[172:175], v150 offset:1024
	ds_read_b128 v[176:179], v150 offset:2048
	ds_read_b128 v[180:183], v150 offset:3072
	s_add_u32 s28, s26, 0xfffc0080
	s_addc_u32 s29, s27, -1
	s_cmp_eq_u32 s84, 12
	s_cselect_b32 s31, s15, s29
	s_cselect_b32 s30, s76, s28
	s_cselect_b32 s29, s13, s83
	s_cselect_b32 s28, s77, s82
	v_lshl_add_u64 v[144:145], s[26:27], 0, v[136:137]
	s_add_i32 m0, s25, 0xc000
	ds_read_b128 v[184:187], v151
	ds_read_b128 v[188:191], v151 offset:1024
	ds_read_b128 v[192:195], v151 offset:2048
	ds_read_b128 v[196:199], v151 offset:3072
	ds_read_b128 v[200:203], v151 offset:4096
	ds_read_b128 v[204:207], v151 offset:5120
	ds_read_b128 v[212:215], v151 offset:6144
	ds_read_b128 v[216:219], v151 offset:7168
	global_load_lds_dwordx4 v[144:145], off
	v_lshl_add_u64 v[144:145], s[26:27], 0, v[138:139]
	s_add_i32 m0, s25, 0xe000
	s_nop 0
	global_load_lds_dwordx4 v[144:145], off
	s_waitcnt vmcnt(8)
	s_waitcnt lgkmcnt(0)
	s_barrier
	s_setprio 1
	s_waitcnt lgkmcnt(0)
	v_mfma_f32_16x16x32_bf16 v[124:127], v[152:155], v[184:187], v[124:127]
	v_mfma_f32_16x16x32_bf16 v[120:123], v[160:163], v[184:187], v[120:123]
	v_mfma_f32_16x16x32_bf16 v[116:119], v[152:155], v[192:195], v[116:119]
	v_mfma_f32_16x16x32_bf16 v[108:111], v[160:163], v[192:195], v[108:111]
	v_mfma_f32_16x16x32_bf16 v[100:103], v[152:155], v[200:203], v[100:103]
	v_mfma_f32_16x16x32_bf16 v[92:95], v[160:163], v[200:203], v[92:95]
	v_mfma_f32_16x16x32_bf16 v[84:87], v[152:155], v[212:215], v[84:87]
	v_mfma_f32_16x16x32_bf16 v[76:79], v[160:163], v[212:215], v[76:79]
	v_mfma_f32_16x16x32_bf16 v[124:127], v[156:159], v[188:191], v[124:127]
	v_mfma_f32_16x16x32_bf16 v[120:123], v[164:167], v[188:191], v[120:123]
	v_mfma_f32_16x16x32_bf16 v[116:119], v[156:159], v[196:199], v[116:119]
	v_mfma_f32_16x16x32_bf16 v[108:111], v[164:167], v[196:199], v[108:111]
	v_mfma_f32_16x16x32_bf16 v[100:103], v[156:159], v[204:207], v[100:103]
	v_mfma_f32_16x16x32_bf16 v[92:95], v[164:167], v[204:207], v[92:95]
	v_mfma_f32_16x16x32_bf16 v[84:87], v[156:159], v[216:219], v[84:87]
	v_mfma_f32_16x16x32_bf16 v[76:79], v[164:167], v[216:219], v[76:79]
	s_setprio 0
	s_setprio 1
	v_mfma_f32_16x16x32_bf16 v[112:115], v[168:171], v[184:187], v[112:115]
	v_mfma_f32_16x16x32_bf16 v[104:107], v[176:179], v[184:187], v[104:107]
	v_mfma_f32_16x16x32_bf16 v[96:99], v[168:171], v[192:195], v[96:99]
	v_mfma_f32_16x16x32_bf16 v[88:91], v[176:179], v[192:195], v[88:91]
	v_mfma_f32_16x16x32_bf16 v[80:83], v[168:171], v[200:203], v[80:83]
	v_mfma_f32_16x16x32_bf16 v[72:75], v[176:179], v[200:203], v[72:75]
	v_mfma_f32_16x16x32_bf16 v[68:71], v[168:171], v[212:215], v[68:71]
	v_mfma_f32_16x16x32_bf16 v[64:67], v[176:179], v[212:215], v[64:67]
	v_mfma_f32_16x16x32_bf16 v[112:115], v[172:175], v[188:191], v[112:115]
	v_mfma_f32_16x16x32_bf16 v[104:107], v[180:183], v[188:191], v[104:107]
	v_mfma_f32_16x16x32_bf16 v[96:99], v[172:175], v[196:199], v[96:99]
	v_mfma_f32_16x16x32_bf16 v[88:91], v[180:183], v[196:199], v[88:91]
	v_mfma_f32_16x16x32_bf16 v[80:83], v[172:175], v[204:207], v[80:83]
	v_mfma_f32_16x16x32_bf16 v[72:75], v[180:183], v[204:207], v[72:75]
	v_mfma_f32_16x16x32_bf16 v[68:71], v[172:175], v[216:219], v[68:71]
	v_mfma_f32_16x16x32_bf16 v[64:67], v[180:183], v[216:219], v[64:67]
	s_setprio 0
	s_barrier
	s_add_i32 s85, s72, s3
	v_lshl_add_u64 v[144:145], s[28:29], 0, v[132:133]
	s_mov_b32 m0, s85
	ds_read_b128 v[184:187], v151 offset:16384
	ds_read_b128 v[188:191], v151 offset:17408
	ds_read_b128 v[192:195], v151 offset:18432
	ds_read_b128 v[196:199], v151 offset:19456
	ds_read_b128 v[200:203], v151 offset:20480
	ds_read_b128 v[204:207], v151 offset:21504
	ds_read_b128 v[212:215], v151 offset:22528
	ds_read_b128 v[216:219], v151 offset:23552
	global_load_lds_dwordx4 v[144:145], off
	s_add_i32 m0, s85, 0x2000
	s_add_u32 s86, s28, 0x40000
	v_lshl_add_u64 v[208:209], s[28:29], 0, v[128:129]
	s_addc_u32 s87, s29, 0
	s_add_i32 s85, s73, s3
	global_load_lds_dwordx4 v[208:209], off
	v_lshl_add_u64 v[220:221], s[86:87], 0, v[132:133]
	s_mov_b32 m0, s85
	v_lshl_add_u64 v[222:223], s[30:31], 0, v[130:131]
	global_load_lds_dwordx4 v[220:221], off
	v_lshl_add_u64 v[220:221], s[86:87], 0, v[128:129]
	s_add_i32 m0, s85, 0x2000
	s_nop 0
	global_load_lds_dwordx4 v[220:221], off
	v_lshl_add_u64 v[220:221], s[30:31], 0, v[134:135]
	s_mov_b32 m0, s25
	s_nop 0
	global_load_lds_dwordx4 v[220:221], off
	s_mov_b32 m0, s50
	s_nop 0
	global_load_lds_dwordx4 v[222:223], off
	s_waitcnt vmcnt(8)
	s_waitcnt lgkmcnt(0)
	s_barrier
; #define PG8_STAGE(bufoff, gbase, voff) do { _Pragma("unroll") for (int _i = 0; _i < 2; ++_i) \
;         __builtin_amdgcn_global_load_lds((const unsigned*)((const char*)(gbase) + (voff)[_i]), (PG8_LAS unsigned*)(lds + (bufoff) + ldsw + _i * 8192), 16, 0, 0); } while (0)
; #define PG8_LDA(dst, b, h) do { _Pragma("unroll") for (int m = 0; m < 4; ++m) _Pragma("unroll") for (int k = 0; k < 2; ++k) dst[m][k] = *(const PG8_LAS bf16x8*)(lds + PG8_SA(b, h) + aoff + m * 2048 + k * 1024); } while (0)
; #define PG8_LDB(dst, b, h) do { _Pragma("unroll") for (int n = 0; n < 2; ++n) _Pragma("unroll") for (int k = 0; k < 2; ++k) dst[n][k] = *(const PG8_LAS bf16x8*)(lds + PG8_SB(b, h) + boff + n * 2048 + k * 1024); } while (0)
; #define PG8_MMA(ai, bj, At, Bt) do { __builtin_amdgcn_s_setprio(1); _Pragma("unroll") for (int m = 0; m < 4; ++m) _Pragma("unroll") for (int n = 0; n < 2; ++n) _Pragma("unroll") for (int k = 0; k < 2; ++k) \
;         acc[ai][bj][m][n] = __builtin_amdgcn_mfma_f32_16x16x32_bf16(Bt[n][k], At[m][k], acc[ai][bj][m][n], 0, 0, 0); __builtin_amdgcn_s_setprio(0); } while (0)
; #define PG8_WAIT_V(n) asm volatile("s_waitcnt vmcnt(" #n ")" ::: "memory")
; #define PG8_WAIT_L(n) asm volatile("s_waitcnt lgkmcnt(" #n ")" ::: "memory")
; #define PG8_BAR __builtin_amdgcn_s_barrier()
; #define PG8_SCHED __builtin_amdgcn_sched_barrier(0)
; template <class Epi, class Sched, bool ALIGN_EPI = false, bool SP2 = false, bool AROWS128 = false>
; __device__ __forceinline__ void gemm_phase(PG8_LAS unsigned char* lds, const Gemm g, const Sched& S, const Epi& E) {
;     ...
;             PG8_WAIT_V(8); PG8_WAIT_L(0); PG8_BAR; PG8_MMA(1, 0, At, B0); PG8_MMA(1, 1, At, B1); PG8_BAR; PG8_SCHED;
;             PG8_LDB(B0, 1, 0); PG8_LDB(B1, 1, 1); PG8_SCHED; PG8_LDA(At, 1, 0); PG8_STAGE(PG8_SA(0, 1), a2 + hstepA, voffA);
;             PG8_WAIT_V(8); PG8_WAIT_L(0); PG8_BAR; PG8_MMA(0, 0, At, B0); PG8_MMA(0, 1, At, B1); PG8_BAR; PG8_SCHED;
	s_setprio 1
	s_waitcnt lgkmcnt(0)
	v_mfma_f32_16x16x32_bf16 v[60:63], v[152:155], v[184:187], v[60:63]
	v_mfma_f32_16x16x32_bf16 v[56:59], v[160:163], v[184:187], v[56:59]
	v_mfma_f32_16x16x32_bf16 v[52:55], v[152:155], v[192:195], v[52:55]
	v_mfma_f32_16x16x32_bf16 v[44:47], v[160:163], v[192:195], v[44:47]
	v_mfma_f32_16x16x32_bf16 v[36:39], v[152:155], v[200:203], v[36:39]
	v_mfma_f32_16x16x32_bf16 v[28:31], v[160:163], v[200:203], v[28:31]
	v_mfma_f32_16x16x32_bf16 v[20:23], v[152:155], v[212:215], v[20:23]
	v_mfma_f32_16x16x32_bf16 v[12:15], v[160:163], v[212:215], v[12:15]
	v_mfma_f32_16x16x32_bf16 v[60:63], v[156:159], v[188:191], v[60:63]
	v_mfma_f32_16x16x32_bf16 v[56:59], v[164:167], v[188:191], v[56:59]
	v_mfma_f32_16x16x32_bf16 v[52:55], v[156:159], v[196:199], v[52:55]
	v_mfma_f32_16x16x32_bf16 v[44:47], v[164:167], v[196:199], v[44:47]
	v_mfma_f32_16x16x32_bf16 v[36:39], v[156:159], v[204:207], v[36:39]
	v_mfma_f32_16x16x32_bf16 v[28:31], v[164:167], v[204:207], v[28:31]
	v_mfma_f32_16x16x32_bf16 v[20:23], v[156:159], v[216:219], v[20:23]
	v_mfma_f32_16x16x32_bf16 v[12:15], v[164:167], v[216:219], v[12:15]
	s_setprio 0
	s_setprio 1
	v_mfma_f32_16x16x32_bf16 v[48:51], v[168:171], v[184:187], v[48:51]
	v_mfma_f32_16x16x32_bf16 v[40:43], v[176:179], v[184:187], v[40:43]
	v_mfma_f32_16x16x32_bf16 v[32:35], v[168:171], v[192:195], v[32:35]
	v_mfma_f32_16x16x32_bf16 v[24:27], v[176:179], v[192:195], v[24:27]
	v_mfma_f32_16x16x32_bf16 v[16:19], v[168:171], v[200:203], v[16:19]
	v_mfma_f32_16x16x32_bf16 v[8:11], v[176:179], v[200:203], v[8:11]
	v_mfma_f32_16x16x32_bf16 v[4:7], v[168:171], v[212:215], v[4:7]
	v_mfma_f32_16x16x32_bf16 v[0:3], v[176:179], v[212:215], v[0:3]
	v_mfma_f32_16x16x32_bf16 v[48:51], v[172:175], v[188:191], v[48:51]
	v_mfma_f32_16x16x32_bf16 v[40:43], v[180:183], v[188:191], v[40:43]
	v_mfma_f32_16x16x32_bf16 v[32:35], v[172:175], v[196:199], v[32:35]
	v_mfma_f32_16x16x32_bf16 v[24:27], v[180:183], v[196:199], v[24:27]
	v_mfma_f32_16x16x32_bf16 v[16:19], v[172:175], v[204:207], v[16:19]
	v_mfma_f32_16x16x32_bf16 v[8:11], v[180:183], v[204:207], v[8:11]
	v_mfma_f32_16x16x32_bf16 v[4:7], v[172:175], v[216:219], v[4:7]
	v_mfma_f32_16x16x32_bf16 v[0:3], v[180:183], v[216:219], v[0:3]
	s_setprio 0
	s_barrier
	s_add_i32 s85, 0, 0x18000
	s_add_i32 s86, 0, 0x1c000
	v_add_u32_e32 v164, s85, v147
	v_add_u32_e32 v180, s86, v147
	ds_read_b128 v[152:155], v164
	ds_read_b128 v[156:159], v164 offset:1024
	ds_read_b128 v[160:163], v164 offset:2048
	ds_read_b128 v[164:167], v164 offset:3072
	ds_read_b128 v[168:171], v180
	ds_read_b128 v[172:175], v180 offset:1024
	ds_read_b128 v[176:179], v180 offset:2048
	ds_read_b128 v[180:183], v180 offset:3072
	s_add_u32 s30, s30, 0x40000
	s_addc_u32 s31, s31, 0
	s_mov_b32 m0, s51
	v_lshl_add_u64 v[224:225], s[30:31], 0, v[134:135]
	ds_read_b128 v[184:187], v151 offset:32768
	ds_read_b128 v[188:191], v151 offset:33792
	ds_read_b128 v[192:195], v151 offset:34816
	ds_read_b128 v[196:199], v151 offset:35840
	ds_read_b128 v[200:203], v151 offset:36864
	ds_read_b128 v[204:207], v151 offset:37888
	ds_read_b128 v[212:215], v151 offset:38912
	ds_read_b128 v[216:219], v151 offset:39936
	global_load_lds_dwordx4 v[224:225], off
	v_lshl_add_u64 v[224:225], s[30:31], 0, v[130:131]
	s_mov_b32 m0, s52
	s_nop 0
	global_load_lds_dwordx4 v[224:225], off
	s_waitcnt vmcnt(8)
	s_waitcnt lgkmcnt(0)
	s_barrier
	s_setprio 1
	s_waitcnt lgkmcnt(0)
	v_mfma_f32_16x16x32_bf16 v[124:127], v[152:155], v[184:187], v[124:127]
	v_mfma_f32_16x16x32_bf16 v[120:123], v[160:163], v[184:187], v[120:123]
	v_mfma_f32_16x16x32_bf16 v[116:119], v[152:155], v[192:195], v[116:119]
	v_mfma_f32_16x16x32_bf16 v[108:111], v[160:163], v[192:195], v[108:111]
	v_mfma_f32_16x16x32_bf16 v[100:103], v[152:155], v[200:203], v[100:103]
	v_mfma_f32_16x16x32_bf16 v[92:95], v[160:163], v[200:203], v[92:95]
	v_mfma_f32_16x16x32_bf16 v[84:87], v[152:155], v[212:215], v[84:87]
	v_mfma_f32_16x16x32_bf16 v[76:79], v[160:163], v[212:215], v[76:79]
	v_mfma_f32_16x16x32_bf16 v[124:127], v[156:159], v[188:191], v[124:127]
	v_mfma_f32_16x16x32_bf16 v[120:123], v[164:167], v[188:191], v[120:123]
	v_mfma_f32_16x16x32_bf16 v[116:119], v[156:159], v[196:199], v[116:119]
	v_mfma_f32_16x16x32_bf16 v[108:111], v[164:167], v[196:199], v[108:111]
	v_mfma_f32_16x16x32_bf16 v[100:103], v[156:159], v[204:207], v[100:103]
	v_mfma_f32_16x16x32_bf16 v[92:95], v[164:167], v[204:207], v[92:95]
	v_mfma_f32_16x16x32_bf16 v[84:87], v[156:159], v[216:219], v[84:87]
	v_mfma_f32_16x16x32_bf16 v[76:79], v[164:167], v[216:219], v[76:79]
	s_setprio 0
	s_setprio 1
	v_mfma_f32_16x16x32_bf16 v[112:115], v[168:171], v[184:187], v[112:115]
	v_mfma_f32_16x16x32_bf16 v[104:107], v[176:179], v[184:187], v[104:107]
	v_mfma_f32_16x16x32_bf16 v[96:99], v[168:171], v[192:195], v[96:99]
	v_mfma_f32_16x16x32_bf16 v[88:91], v[176:179], v[192:195], v[88:91]
	v_mfma_f32_16x16x32_bf16 v[80:83], v[168:171], v[200:203], v[80:83]
	v_mfma_f32_16x16x32_bf16 v[72:75], v[176:179], v[200:203], v[72:75]
	v_mfma_f32_16x16x32_bf16 v[68:71], v[168:171], v[212:215], v[68:71]
	v_mfma_f32_16x16x32_bf16 v[64:67], v[176:179], v[212:215], v[64:67]
	v_mfma_f32_16x16x32_bf16 v[112:115], v[172:175], v[188:191], v[112:115]
	v_mfma_f32_16x16x32_bf16 v[104:107], v[180:183], v[188:191], v[104:107]
	v_mfma_f32_16x16x32_bf16 v[96:99], v[172:175], v[196:199], v[96:99]
	v_mfma_f32_16x16x32_bf16 v[88:91], v[180:183], v[196:199], v[88:91]
	v_mfma_f32_16x16x32_bf16 v[80:83], v[172:175], v[204:207], v[80:83]
	v_mfma_f32_16x16x32_bf16 v[72:75], v[180:183], v[204:207], v[72:75]
	v_mfma_f32_16x16x32_bf16 v[68:71], v[172:175], v[216:219], v[68:71]
	v_mfma_f32_16x16x32_bf16 v[64:67], v[180:183], v[216:219], v[64:67]
	s_setprio 0
	s_barrier
; #define PG8_STAGE(bufoff, gbase, voff) do { _Pragma("unroll") for (int _i = 0; _i < 2; ++_i) \
;         __builtin_amdgcn_global_load_lds((const unsigned*)((const char*)(gbase) + (voff)[_i]), (PG8_LAS unsigned*)(lds + (bufoff) + ldsw + _i * 8192), 16, 0, 0); } while (0)
; #define PG8_LDA(dst, b, h) do { _Pragma("unroll") for (int m = 0; m < 4; ++m) _Pragma("unroll") for (int k = 0; k < 2; ++k) dst[m][k] = *(const PG8_LAS bf16x8*)(lds + PG8_SA(b, h) + aoff + m * 2048 + k * 1024); } while (0)
; #define PG8_MMA(ai, bj, At, Bt) do { __builtin_amdgcn_s_setprio(1); _Pragma("unroll") for (int m = 0; m < 4; ++m) _Pragma("unroll") for (int n = 0; n < 2; ++n) _Pragma("unroll") for (int k = 0; k < 2; ++k) \
;         acc[ai][bj][m][n] = __builtin_amdgcn_mfma_f32_16x16x32_bf16(Bt[n][k], At[m][k], acc[ai][bj][m][n], 0, 0, 0); __builtin_amdgcn_s_setprio(0); } while (0)
; #define PG8_WAIT_V(n) asm volatile("s_waitcnt vmcnt(" #n ")" ::: "memory")
; #define PG8_WAIT_L(n) asm volatile("s_waitcnt lgkmcnt(" #n ")" ::: "memory")
; #define PG8_BAR __builtin_amdgcn_s_barrier()
; #define PG8_SCHED __builtin_amdgcn_sched_barrier(0)
; template <class Epi, class Sched, bool ALIGN_EPI = false, bool SP2 = false, bool AROWS128 = false>
; __device__ __forceinline__ void gemm_phase(PG8_LAS unsigned char* lds, const Gemm g, const Sched& S, const Epi& E) {
;     ...
;         for (int t = 0; t < nt; t += 2) {
;     ...
;             PG8_LDA(At, 1, 1); PG8_STAGE(PG8_SB(1, 0), b3, voffB); PG8_STAGE(PG8_SB(1, 1), b3 + hstep, voffB); PG8_STAGE(PG8_SA(1, 0), a3, voffA);
;             PG8_WAIT_V(8); PG8_WAIT_L(0); PG8_BAR; PG8_MMA(1, 0, At, B0); PG8_MMA(1, 1, At, B1); PG8_BAR; PG8_SCHED;
	s_add_i32 s30, s85, s3
	v_lshl_add_u64 v[144:145], v[144:145], 0, s[6:7]
	s_mov_b32 m0, s30
	ds_read_b128 v[184:187], v151 offset:49152
	ds_read_b128 v[188:191], v151 offset:50176
	ds_read_b128 v[192:195], v151 offset:51200
	ds_read_b128 v[196:199], v151 offset:52224
	ds_read_b128 v[200:203], v151 offset:53248
	ds_read_b128 v[204:207], v151 offset:54272
	ds_read_b128 v[212:215], v151 offset:55296
	ds_read_b128 v[216:219], v151 offset:56320
	global_load_lds_dwordx4 v[144:145], off
	s_add_i32 m0, s30, 0x2000
	s_add_u32 s28, s28, 0x40080
	v_lshl_add_u64 v[144:145], v[208:209], 0, s[6:7]
	s_addc_u32 s29, s29, 0
	s_add_i32 s30, s86, s3
	global_load_lds_dwordx4 v[144:145], off
	v_lshl_add_u64 v[144:145], s[28:29], 0, v[132:133]
	s_mov_b32 m0, s30
	s_nop 0
	global_load_lds_dwordx4 v[144:145], off
	v_lshl_add_u64 v[144:145], s[28:29], 0, v[128:129]
	s_add_i32 m0, s30, 0x2000
	s_nop 0
	global_load_lds_dwordx4 v[144:145], off
	v_lshl_add_u64 v[144:145], v[220:221], 0, s[6:7]
	s_mov_b32 m0, s58
	s_nop 0
	global_load_lds_dwordx4 v[144:145], off
	v_lshl_add_u64 v[144:145], v[222:223], 0, s[6:7]
	s_mov_b32 m0, s59
	s_nop 0
	global_load_lds_dwordx4 v[144:145], off
	s_waitcnt vmcnt(8)
	s_waitcnt lgkmcnt(0)
	s_barrier
	s_setprio 1
	s_waitcnt lgkmcnt(0)
	v_mfma_f32_16x16x32_bf16 v[60:63], v[152:155], v[184:187], v[60:63]
	v_mfma_f32_16x16x32_bf16 v[56:59], v[160:163], v[184:187], v[56:59]
	v_mfma_f32_16x16x32_bf16 v[52:55], v[152:155], v[192:195], v[52:55]
	v_mfma_f32_16x16x32_bf16 v[44:47], v[160:163], v[192:195], v[44:47]
	v_mfma_f32_16x16x32_bf16 v[36:39], v[152:155], v[200:203], v[36:39]
	v_mfma_f32_16x16x32_bf16 v[28:31], v[160:163], v[200:203], v[28:31]
	v_mfma_f32_16x16x32_bf16 v[20:23], v[152:155], v[212:215], v[20:23]
	v_mfma_f32_16x16x32_bf16 v[12:15], v[160:163], v[212:215], v[12:15]
	v_mfma_f32_16x16x32_bf16 v[60:63], v[156:159], v[188:191], v[60:63]
	v_mfma_f32_16x16x32_bf16 v[56:59], v[164:167], v[188:191], v[56:59]
	v_mfma_f32_16x16x32_bf16 v[52:55], v[156:159], v[196:199], v[52:55]
	v_mfma_f32_16x16x32_bf16 v[44:47], v[164:167], v[196:199], v[44:47]
	v_mfma_f32_16x16x32_bf16 v[36:39], v[156:159], v[204:207], v[36:39]
	v_mfma_f32_16x16x32_bf16 v[28:31], v[164:167], v[204:207], v[28:31]
	v_mfma_f32_16x16x32_bf16 v[20:23], v[156:159], v[216:219], v[20:23]
	v_mfma_f32_16x16x32_bf16 v[12:15], v[164:167], v[216:219], v[12:15]
	s_setprio 0
	s_setprio 1
	v_mfma_f32_16x16x32_bf16 v[48:51], v[168:171], v[184:187], v[48:51]
	v_mfma_f32_16x16x32_bf16 v[40:43], v[176:179], v[184:187], v[40:43]
	v_mfma_f32_16x16x32_bf16 v[32:35], v[168:171], v[192:195], v[32:35]
	v_mfma_f32_16x16x32_bf16 v[24:27], v[176:179], v[192:195], v[24:27]
	v_mfma_f32_16x16x32_bf16 v[16:19], v[168:171], v[200:203], v[16:19]
	v_mfma_f32_16x16x32_bf16 v[8:11], v[176:179], v[200:203], v[8:11]
	v_mfma_f32_16x16x32_bf16 v[4:7], v[168:171], v[212:215], v[4:7]
	v_mfma_f32_16x16x32_bf16 v[0:3], v[176:179], v[212:215], v[0:3]
	v_mfma_f32_16x16x32_bf16 v[48:51], v[172:175], v[188:191], v[48:51]
	v_mfma_f32_16x16x32_bf16 v[40:43], v[180:183], v[188:191], v[40:43]
	v_mfma_f32_16x16x32_bf16 v[32:35], v[172:175], v[196:199], v[32:35]
	v_mfma_f32_16x16x32_bf16 v[24:27], v[180:183], v[196:199], v[24:27]
	v_mfma_f32_16x16x32_bf16 v[16:19], v[172:175], v[204:207], v[16:19]
	v_mfma_f32_16x16x32_bf16 v[8:11], v[180:183], v[204:207], v[8:11]
	v_mfma_f32_16x16x32_bf16 v[4:7], v[172:175], v[216:219], v[4:7]
	v_mfma_f32_16x16x32_bf16 v[0:3], v[180:183], v[216:219], v[0:3]
	s_setprio 0
	s_add_i32 s84, s84, 2
	s_add_u32 s26, s26, 0x100
	s_addc_u32 s27, s27, 0
	s_add_u32 s82, s82, 0x100
	s_addc_u32 s83, s83, 0
	s_cmp_gt_u32 s84, 13
	s_cbranch_scc0 .Lrot_k1
	s_barrier
	s_and_b64 vcc, exec, s[8:9]
	s_cbranch_vccz .LBB0_492
	s_barrier

; template <class Epi, class Sched, bool ALIGN_EPI = false, bool SP2 = false, bool AROWS128 = false>
; __device__ __forceinline__ void gemm_phase(PG8_LAS unsigned char* lds, const Gemm g, const Sched& S, const Epi& E) {
;     ...
;         const bool has_next = S.next(ui + 1, nxt);
;         const char* nA = has_next ? (const char*)g.A + (size_t)nxt.pm * tstep : cA; const char* nB = has_next ? (const char*)g.Bt + (size_t)nxt.pn * tstep : cB;
;     ...
; #pragma unroll
;         for (int a = 0; a < 2; ++a)
; #pragma unroll
;             for (int b = 0; b < 2; ++b)
; #pragma unroll
;                 for (int m = 0; m < 4; ++m)
; #pragma unroll
;                     for (int n = 0; n < 2; ++n) acc[a][b][m][n] = (f32x4){0.f, 0.f, 0.f, 0.f};
.LBB0_625:
	v_mov_b32_e32 v236, s16
	v_lshlrev_b32_e32 v236, 9, v236
	v_mov_b32_e32 v237, 0
	v_lshl_add_u64 v[232:233], v[230:231], 0, v[236:237]
	s_lshr_b32 m0, s84, 1
	s_add_i32 m0, m0, 0x21000
	s_mov_b32 exec_hi, 0
	global_load_lds_dwordx4 v[232:233], off
	s_mov_b32 exec_hi, -1
	s_ashr_i32 s55, s54, 31
	s_lshl_b64 s[56:57], s[54:55], 19
	s_add_u32 s56, s46, s56
	s_addc_u32 s57, s47, s57
	s_and_b64 s[58:59], s[14:15], exec
	s_cselect_b32 s17, s57, s19
	s_cselect_b32 s33, s56, s18
	s_ashr_i32 s53, s52, 31
	s_lshl_b64 s[58:59], s[52:53], 19
	s_add_u32 s58, s78, s58
	s_addc_u32 s59, s79, s59
	s_and_b64 s[72:73], s[14:15], exec
	s_cselect_b32 s53, s59, s21
	s_cselect_b32 s55, s58, s20
	s_add_u32 s18, s18, 0x20080
	s_addc_u32 s19, s19, 0
	s_add_u32 s65, s20, 0x100
	v_mov_b32_e32 v0, 0
	s_addc_u32 s72, s21, 0
	s_mov_b32 s73, -2
	v_mov_b64_e32 v[0:1], 0
	v_mov_b64_e32 v[2:3], 0
	v_mov_b64_e32 v[4:5], 0
	v_mov_b64_e32 v[6:7], 0
	v_mov_b64_e32 v[8:9], 0
	v_mov_b64_e32 v[10:11], 0
	v_mov_b64_e32 v[12:13], 0
	v_mov_b64_e32 v[14:15], 0
	v_mov_b64_e32 v[16:17], 0
	v_mov_b64_e32 v[18:19], 0
	v_mov_b64_e32 v[20:21], 0
	v_mov_b64_e32 v[22:23], 0
	v_mov_b64_e32 v[24:25], 0
	v_mov_b64_e32 v[26:27], 0
	v_mov_b64_e32 v[28:29], 0
	v_mov_b64_e32 v[30:31], 0
	v_mov_b64_e32 v[32:33], 0
	v_mov_b64_e32 v[34:35], 0
	v_mov_b64_e32 v[36:37], 0
	v_mov_b64_e32 v[38:39], 0
	v_mov_b64_e32 v[40:41], 0
	v_mov_b64_e32 v[42:43], 0
	v_mov_b64_e32 v[44:45], 0
	v_mov_b64_e32 v[46:47], 0
	v_mov_b64_e32 v[48:49], 0
	v_mov_b64_e32 v[50:51], 0
	v_mov_b64_e32 v[52:53], 0
	v_mov_b64_e32 v[54:55], 0
	v_mov_b64_e32 v[56:57], 0
	v_mov_b64_e32 v[58:59], 0
	v_mov_b64_e32 v[60:61], 0
	v_mov_b64_e32 v[62:63], 0
	v_mov_b64_e32 v[64:65], 0
	v_mov_b64_e32 v[66:67], 0
	v_mov_b64_e32 v[68:69], 0
	v_mov_b64_e32 v[70:71], 0
	v_mov_b64_e32 v[104:105], 0
	v_mov_b64_e32 v[106:107], 0
	v_mov_b64_e32 v[108:109], 0
	v_mov_b64_e32 v[110:111], 0
	v_mov_b64_e32 v[112:113], 0
	v_mov_b64_e32 v[114:115], 0
	v_mov_b64_e32 v[116:117], 0
	v_mov_b64_e32 v[118:119], 0
	v_mov_b64_e32 v[120:121], 0
	v_mov_b64_e32 v[122:123], 0
	v_mov_b64_e32 v[124:125], 0
	v_mov_b64_e32 v[126:127], 0
	v_mov_b64_e32 v[128:129], 0
	v_mov_b64_e32 v[130:131], 0
	v_mov_b64_e32 v[132:133], 0
	v_mov_b64_e32 v[134:135], 0
	v_mov_b64_e32 v[136:137], 0
	v_mov_b64_e32 v[138:139], 0
	v_mov_b64_e32 v[140:141], 0
	v_mov_b64_e32 v[142:143], 0
	v_mov_b64_e32 v[144:145], 0
	v_mov_b64_e32 v[146:147], 0
	v_mov_b64_e32 v[148:149], 0
	v_mov_b64_e32 v[150:151], 0
	v_mov_b64_e32 v[152:153], 0
	v_mov_b64_e32 v[154:155], 0
	v_mov_b64_e32 v[156:157], 0
	v_mov_b64_e32 v[158:159], 0
	s_branch .LBB0_626

; #define PG8_STAGE(bufoff, gbase, voff) do { _Pragma("unroll") for (int _i = 0; _i < 2; ++_i) \
;         __builtin_amdgcn_global_load_lds((const unsigned*)((const char*)(gbase) + (voff)[_i]), (PG8_LAS unsigned*)(lds + (bufoff) + ldsw + _i * 8192), 16, 0, 0); } while (0)
; #define PG8_LDA(dst, b, h) do { _Pragma("unroll") for (int m = 0; m < 4; ++m) _Pragma("unroll") for (int k = 0; k < 2; ++k) dst[m][k] = *(const PG8_LAS bf16x8*)(lds + PG8_SA(b, h) + aoff + m * 2048 + k * 1024); } while (0)
; #define PG8_LDB(dst, b, h) do { _Pragma("unroll") for (int n = 0; n < 2; ++n) _Pragma("unroll") for (int k = 0; k < 2; ++k) dst[n][k] = *(const PG8_LAS bf16x8*)(lds + PG8_SB(b, h) + boff + n * 2048 + k * 1024); } while (0)
; #define PG8_MMA(ai, bj, At, Bt) do { __builtin_amdgcn_s_setprio(1); _Pragma("unroll") for (int m = 0; m < 4; ++m) _Pragma("unroll") for (int n = 0; n < 2; ++n) _Pragma("unroll") for (int k = 0; k < 2; ++k) \
;         acc[ai][bj][m][n] = __builtin_amdgcn_mfma_f32_16x16x32_bf16(Bt[n][k], At[m][k], acc[ai][bj][m][n], 0, 0, 0); __builtin_amdgcn_s_setprio(0); } while (0)
; #define PG8_WAIT_V(n) asm volatile("s_waitcnt vmcnt(" #n ")" ::: "memory")
; #define PG8_WAIT_L(n) asm volatile("s_waitcnt lgkmcnt(" #n ")" ::: "memory")
; #define PG8_BAR __builtin_amdgcn_s_barrier()
; #define PG8_SCHED __builtin_amdgcn_sched_barrier(0)
; template <class Epi, class Sched, bool ALIGN_EPI = false, bool SP2 = false, bool AROWS128 = false>
; __device__ __forceinline__ void gemm_phase(PG8_LAS unsigned char* lds, const Gemm g, const Sched& S, const Epi& E) {
;     ...
;             PG8_LDB(B0, 0, 0); PG8_LDB(B1, 0, 1); PG8_SCHED; PG8_LDA(At, 0, 0); PG8_STAGE(PG8_SA(1, 1), a1 + hstepA, voffA);
;             PG8_WAIT_V(8); PG8_WAIT_L(0); PG8_BAR; PG8_MMA(0, 0, At, B0); PG8_MMA(0, 1, At, B1); PG8_BAR; PG8_SCHED;
;             PG8_LDA(At, 0, 1); PG8_STAGE(PG8_SB(0, 0), b2, voffB); PG8_STAGE(PG8_SB(0, 1), b2 + hstep, voffB); PG8_STAGE(PG8_SA(0, 0), a2, voffA);
;             PG8_WAIT_V(8); PG8_WAIT_L(0); PG8_BAR; PG8_MMA(1, 0, At, B0); PG8_MMA(1, 1, At, B1); PG8_BAR; PG8_SCHED;
;             PG8_LDB(B0, 1, 0); PG8_LDB(B1, 1, 1); PG8_SCHED; PG8_LDA(At, 1, 0); PG8_STAGE(PG8_SA(0, 1), a2 + hstepA, voffA);
;             PG8_WAIT_V(8); PG8_WAIT_L(0); PG8_BAR; PG8_MMA(0, 0, At, B0); PG8_MMA(0, 1, At, B1); PG8_BAR; PG8_SCHED;
.LBB0_626:
	ds_read_b128 v[72:75], v207
	ds_read_b128 v[76:79], v207 offset:1024
	ds_read_b128 v[80:83], v207 offset:2048
	ds_read_b128 v[84:87], v207 offset:3072
	ds_read_b128 v[88:91], v208
	ds_read_b128 v[92:95], v208 offset:1024
	ds_read_b128 v[96:99], v208 offset:2048
	ds_read_b128 v[100:103], v208 offset:3072
	s_add_u32 s20, s18, 0xfffe0080
	s_addc_u32 s21, s19, -1
	s_cmp_eq_u32 s73, 12
	s_cselect_b32 s81, s17, s21
	s_cselect_b32 s80, s33, s20
	s_cselect_b32 s21, s53, s72
	s_cselect_b32 s20, s55, s65
	v_lshl_add_u64 v[220:221], s[18:19], 0, v[168:169]
	s_add_i32 m0, s84, 0xc000
	ds_read_b128 v[176:179], v209
	ds_read_b128 v[180:183], v209 offset:1024
	ds_read_b128 v[184:187], v209 offset:2048
	ds_read_b128 v[188:191], v209 offset:3072
	ds_read_b128 v[192:195], v209 offset:4096
	ds_read_b128 v[196:199], v209 offset:5120
	ds_read_b128 v[212:215], v209 offset:6144
	ds_read_b128 v[216:219], v209 offset:7168
	global_load_lds_dwordx4 v[220:221], off
	v_lshl_add_u64 v[220:221], s[18:19], 0, v[170:171]
	s_add_i32 m0, s84, 0xe000
	s_nop 0
	global_load_lds_dwordx4 v[220:221], off
	s_waitcnt vmcnt(8)
	s_waitcnt lgkmcnt(0)
	s_barrier
	s_setprio 1
	s_waitcnt lgkmcnt(0)
	v_mfma_f32_16x16x32_bf16 v[36:39], v[72:75], v[176:179], v[36:39]
	v_mfma_f32_16x16x32_bf16 v[28:31], v[80:83], v[176:179], v[28:31]
	v_mfma_f32_16x16x32_bf16 v[140:143], v[72:75], v[184:187], v[140:143]
	v_mfma_f32_16x16x32_bf16 v[136:139], v[80:83], v[184:187], v[136:139]
	v_mfma_f32_16x16x32_bf16 v[124:127], v[72:75], v[192:195], v[124:127]
	v_mfma_f32_16x16x32_bf16 v[120:123], v[80:83], v[192:195], v[120:123]
	v_mfma_f32_16x16x32_bf16 v[108:111], v[72:75], v[212:215], v[108:111]
	v_mfma_f32_16x16x32_bf16 v[104:107], v[80:83], v[212:215], v[104:107]
	v_mfma_f32_16x16x32_bf16 v[36:39], v[76:79], v[180:183], v[36:39]
	v_mfma_f32_16x16x32_bf16 v[28:31], v[84:87], v[180:183], v[28:31]
	v_mfma_f32_16x16x32_bf16 v[140:143], v[76:79], v[188:191], v[140:143]
	v_mfma_f32_16x16x32_bf16 v[136:139], v[84:87], v[188:191], v[136:139]
	v_mfma_f32_16x16x32_bf16 v[124:127], v[76:79], v[196:199], v[124:127]
	v_mfma_f32_16x16x32_bf16 v[120:123], v[84:87], v[196:199], v[120:123]
	v_mfma_f32_16x16x32_bf16 v[108:111], v[76:79], v[216:219], v[108:111]
	v_mfma_f32_16x16x32_bf16 v[104:107], v[84:87], v[216:219], v[104:107]
	s_setprio 0
	s_setprio 1
	v_mfma_f32_16x16x32_bf16 v[156:159], v[88:91], v[176:179], v[156:159]
	v_mfma_f32_16x16x32_bf16 v[152:155], v[96:99], v[176:179], v[152:155]
	v_mfma_f32_16x16x32_bf16 v[148:151], v[88:91], v[184:187], v[148:151]
	v_mfma_f32_16x16x32_bf16 v[144:147], v[96:99], v[184:187], v[144:147]
	v_mfma_f32_16x16x32_bf16 v[132:135], v[88:91], v[192:195], v[132:135]
	v_mfma_f32_16x16x32_bf16 v[128:131], v[96:99], v[192:195], v[128:131]
	v_mfma_f32_16x16x32_bf16 v[116:119], v[88:91], v[212:215], v[116:119]
	v_mfma_f32_16x16x32_bf16 v[112:115], v[96:99], v[212:215], v[112:115]
	v_mfma_f32_16x16x32_bf16 v[156:159], v[92:95], v[180:183], v[156:159]
	v_mfma_f32_16x16x32_bf16 v[152:155], v[100:103], v[180:183], v[152:155]
	v_mfma_f32_16x16x32_bf16 v[148:151], v[92:95], v[188:191], v[148:151]
	v_mfma_f32_16x16x32_bf16 v[144:147], v[100:103], v[188:191], v[144:147]
	v_mfma_f32_16x16x32_bf16 v[132:135], v[92:95], v[196:199], v[132:135]
	v_mfma_f32_16x16x32_bf16 v[128:131], v[100:103], v[196:199], v[128:131]
	v_mfma_f32_16x16x32_bf16 v[116:119], v[92:95], v[216:219], v[116:119]
	v_mfma_f32_16x16x32_bf16 v[112:115], v[100:103], v[216:219], v[112:115]
	s_setprio 0
	s_barrier
	s_add_i32 s76, s3, s35
	v_lshl_add_u64 v[220:221], s[20:21], 0, v[162:163]
	s_mov_b32 m0, s76
	ds_read_b128 v[176:179], v209 offset:16384
	ds_read_b128 v[180:183], v209 offset:17408
	ds_read_b128 v[184:187], v209 offset:18432
	ds_read_b128 v[188:191], v209 offset:19456
	ds_read_b128 v[192:195], v209 offset:20480
	ds_read_b128 v[196:199], v209 offset:21504
	ds_read_b128 v[212:215], v209 offset:22528
	ds_read_b128 v[216:219], v209 offset:23552
	global_load_lds_dwordx4 v[220:221], off
	s_add_i32 m0, s76, 0x2000
	s_add_u32 s76, s20, 0x40000
	v_lshl_add_u64 v[222:223], s[20:21], 0, v[166:167]
	s_addc_u32 s77, s21, 0
	s_add_i32 s82, s95, s35
	global_load_lds_dwordx4 v[222:223], off
	v_lshl_add_u64 v[224:225], s[76:77], 0, v[162:163]
	s_mov_b32 m0, s82
	v_lshl_add_u64 v[226:227], s[80:81], 0, v[164:165]
	global_load_lds_dwordx4 v[224:225], off
	v_lshl_add_u64 v[224:225], s[76:77], 0, v[166:167]
	s_add_i32 m0, s82, 0x2000
	s_nop 0
	global_load_lds_dwordx4 v[224:225], off
	v_lshl_add_u64 v[224:225], s[80:81], 0, v[160:161]
	s_mov_b32 m0, s84
	s_nop 0
	global_load_lds_dwordx4 v[224:225], off
	s_mov_b32 m0, s85
	s_nop 0
	global_load_lds_dwordx4 v[226:227], off
	s_waitcnt vmcnt(8)
	s_waitcnt lgkmcnt(0)
	s_barrier
; #define PG8_STAGE(bufoff, gbase, voff) do { _Pragma("unroll") for (int _i = 0; _i < 2; ++_i) \
;         __builtin_amdgcn_global_load_lds((const unsigned*)((const char*)(gbase) + (voff)[_i]), (PG8_LAS unsigned*)(lds + (bufoff) + ldsw + _i * 8192), 16, 0, 0); } while (0)
; #define PG8_LDA(dst, b, h) do { _Pragma("unroll") for (int m = 0; m < 4; ++m) _Pragma("unroll") for (int k = 0; k < 2; ++k) dst[m][k] = *(const PG8_LAS bf16x8*)(lds + PG8_SA(b, h) + aoff + m * 2048 + k * 1024); } while (0)
; #define PG8_LDB(dst, b, h) do { _Pragma("unroll") for (int n = 0; n < 2; ++n) _Pragma("unroll") for (int k = 0; k < 2; ++k) dst[n][k] = *(const PG8_LAS bf16x8*)(lds + PG8_SB(b, h) + boff + n * 2048 + k * 1024); } while (0)
; #define PG8_MMA(ai, bj, At, Bt) do { __builtin_amdgcn_s_setprio(1); _Pragma("unroll") for (int m = 0; m < 4; ++m) _Pragma("unroll") for (int n = 0; n < 2; ++n) _Pragma("unroll") for (int k = 0; k < 2; ++k) \
;         acc[ai][bj][m][n] = __builtin_amdgcn_mfma_f32_16x16x32_bf16(Bt[n][k], At[m][k], acc[ai][bj][m][n], 0, 0, 0); __builtin_amdgcn_s_setprio(0); } while (0)
; #define PG8_WAIT_V(n) asm volatile("s_waitcnt vmcnt(" #n ")" ::: "memory")
; #define PG8_WAIT_L(n) asm volatile("s_waitcnt lgkmcnt(" #n ")" ::: "memory")
; #define PG8_BAR __builtin_amdgcn_s_barrier()
; #define PG8_SCHED __builtin_amdgcn_sched_barrier(0)
; template <class Epi, class Sched, bool ALIGN_EPI = false, bool SP2 = false, bool AROWS128 = false>
; __device__ __forceinline__ void gemm_phase(PG8_LAS unsigned char* lds, const Gemm g, const Sched& S, const Epi& E) {
;     ...
;             PG8_WAIT_V(8); PG8_WAIT_L(0); PG8_BAR; PG8_MMA(1, 0, At, B0); PG8_MMA(1, 1, At, B1); PG8_BAR; PG8_SCHED;
;             PG8_LDB(B0, 1, 0); PG8_LDB(B1, 1, 1); PG8_SCHED; PG8_LDA(At, 1, 0); PG8_STAGE(PG8_SA(0, 1), a2 + hstepA, voffA);
;             PG8_WAIT_V(8); PG8_WAIT_L(0); PG8_BAR; PG8_MMA(0, 0, At, B0); PG8_MMA(0, 1, At, B1); PG8_BAR; PG8_SCHED;
	s_setprio 1
	s_waitcnt lgkmcnt(0)
	v_mfma_f32_16x16x32_bf16 v[60:63], v[72:75], v[176:179], v[60:63]
	v_mfma_f32_16x16x32_bf16 v[56:59], v[80:83], v[176:179], v[56:59]
	v_mfma_f32_16x16x32_bf16 v[44:47], v[72:75], v[184:187], v[44:47]
	v_mfma_f32_16x16x32_bf16 v[40:43], v[80:83], v[184:187], v[40:43]
	v_mfma_f32_16x16x32_bf16 v[20:23], v[72:75], v[192:195], v[20:23]
	v_mfma_f32_16x16x32_bf16 v[16:19], v[80:83], v[192:195], v[16:19]
	v_mfma_f32_16x16x32_bf16 v[12:15], v[72:75], v[212:215], v[12:15]
	v_mfma_f32_16x16x32_bf16 v[8:11], v[80:83], v[212:215], v[8:11]
	v_mfma_f32_16x16x32_bf16 v[60:63], v[76:79], v[180:183], v[60:63]
	v_mfma_f32_16x16x32_bf16 v[56:59], v[84:87], v[180:183], v[56:59]
	v_mfma_f32_16x16x32_bf16 v[44:47], v[76:79], v[188:191], v[44:47]
	v_mfma_f32_16x16x32_bf16 v[40:43], v[84:87], v[188:191], v[40:43]
	v_mfma_f32_16x16x32_bf16 v[20:23], v[76:79], v[196:199], v[20:23]
	v_mfma_f32_16x16x32_bf16 v[16:19], v[84:87], v[196:199], v[16:19]
	v_mfma_f32_16x16x32_bf16 v[12:15], v[76:79], v[216:219], v[12:15]
	v_mfma_f32_16x16x32_bf16 v[8:11], v[84:87], v[216:219], v[8:11]
	s_setprio 0
	s_setprio 1
	v_mfma_f32_16x16x32_bf16 v[68:71], v[88:91], v[176:179], v[68:71]
	v_mfma_f32_16x16x32_bf16 v[64:67], v[96:99], v[176:179], v[64:67]
	v_mfma_f32_16x16x32_bf16 v[52:55], v[88:91], v[184:187], v[52:55]
	v_mfma_f32_16x16x32_bf16 v[48:51], v[96:99], v[184:187], v[48:51]
	v_mfma_f32_16x16x32_bf16 v[32:35], v[88:91], v[192:195], v[32:35]
	v_mfma_f32_16x16x32_bf16 v[24:27], v[96:99], v[192:195], v[24:27]
	v_mfma_f32_16x16x32_bf16 v[4:7], v[88:91], v[212:215], v[4:7]
	v_mfma_f32_16x16x32_bf16 v[0:3], v[96:99], v[212:215], v[0:3]
	v_mfma_f32_16x16x32_bf16 v[68:71], v[92:95], v[180:183], v[68:71]
	v_mfma_f32_16x16x32_bf16 v[64:67], v[100:103], v[180:183], v[64:67]
	v_mfma_f32_16x16x32_bf16 v[52:55], v[92:95], v[188:191], v[52:55]
	v_mfma_f32_16x16x32_bf16 v[48:51], v[100:103], v[188:191], v[48:51]
	v_mfma_f32_16x16x32_bf16 v[32:35], v[92:95], v[196:199], v[32:35]
	v_mfma_f32_16x16x32_bf16 v[24:27], v[100:103], v[196:199], v[24:27]
	v_mfma_f32_16x16x32_bf16 v[4:7], v[92:95], v[216:219], v[4:7]
	v_mfma_f32_16x16x32_bf16 v[0:3], v[100:103], v[216:219], v[0:3]
	s_setprio 0
	s_barrier
	s_add_i32 s82, 0, 0x18000
	s_add_i32 s83, 0, 0x1c000
	v_add_u32_e32 v84, s82, v200
	v_add_u32_e32 v100, s83, v200
	ds_read_b128 v[72:75], v84
	ds_read_b128 v[76:79], v84 offset:1024
	ds_read_b128 v[80:83], v84 offset:2048
	ds_read_b128 v[84:87], v84 offset:3072
	ds_read_b128 v[88:91], v100
	ds_read_b128 v[92:95], v100 offset:1024
	ds_read_b128 v[96:99], v100 offset:2048
	ds_read_b128 v[100:103], v100 offset:3072
	s_add_u32 s76, s80, 0x20000
	s_addc_u32 s77, s81, 0
	s_mov_b32 m0, s86
	v_lshl_add_u64 v[228:229], s[76:77], 0, v[160:161]
	ds_read_b128 v[176:179], v209 offset:32768
	ds_read_b128 v[180:183], v209 offset:33792
	ds_read_b128 v[184:187], v209 offset:34816
	ds_read_b128 v[188:191], v209 offset:35840
	ds_read_b128 v[192:195], v209 offset:36864
	ds_read_b128 v[196:199], v209 offset:37888
	ds_read_b128 v[212:215], v209 offset:38912
	ds_read_b128 v[216:219], v209 offset:39936
	global_load_lds_dwordx4 v[228:229], off
	v_lshl_add_u64 v[228:229], s[76:77], 0, v[164:165]
	s_mov_b32 m0, s87
	s_nop 0
	global_load_lds_dwordx4 v[228:229], off
	s_waitcnt vmcnt(8)
	s_waitcnt lgkmcnt(0)
	s_barrier
	s_setprio 1
	s_waitcnt lgkmcnt(0)
	v_mfma_f32_16x16x32_bf16 v[36:39], v[72:75], v[176:179], v[36:39]
	v_mfma_f32_16x16x32_bf16 v[28:31], v[80:83], v[176:179], v[28:31]
	v_mfma_f32_16x16x32_bf16 v[140:143], v[72:75], v[184:187], v[140:143]
	v_mfma_f32_16x16x32_bf16 v[136:139], v[80:83], v[184:187], v[136:139]
	v_mfma_f32_16x16x32_bf16 v[124:127], v[72:75], v[192:195], v[124:127]
	v_mfma_f32_16x16x32_bf16 v[120:123], v[80:83], v[192:195], v[120:123]
	v_mfma_f32_16x16x32_bf16 v[108:111], v[72:75], v[212:215], v[108:111]
	v_mfma_f32_16x16x32_bf16 v[104:107], v[80:83], v[212:215], v[104:107]
	v_mfma_f32_16x16x32_bf16 v[36:39], v[76:79], v[180:183], v[36:39]
	v_mfma_f32_16x16x32_bf16 v[28:31], v[84:87], v[180:183], v[28:31]
	v_mfma_f32_16x16x32_bf16 v[140:143], v[76:79], v[188:191], v[140:143]
	v_mfma_f32_16x16x32_bf16 v[136:139], v[84:87], v[188:191], v[136:139]
	v_mfma_f32_16x16x32_bf16 v[124:127], v[76:79], v[196:199], v[124:127]
	v_mfma_f32_16x16x32_bf16 v[120:123], v[84:87], v[196:199], v[120:123]
	v_mfma_f32_16x16x32_bf16 v[108:111], v[76:79], v[216:219], v[108:111]
	v_mfma_f32_16x16x32_bf16 v[104:107], v[84:87], v[216:219], v[104:107]
	s_setprio 0
	s_setprio 1
	v_mfma_f32_16x16x32_bf16 v[156:159], v[88:91], v[176:179], v[156:159]
	v_mfma_f32_16x16x32_bf16 v[152:155], v[96:99], v[176:179], v[152:155]
	v_mfma_f32_16x16x32_bf16 v[148:151], v[88:91], v[184:187], v[148:151]
	v_mfma_f32_16x16x32_bf16 v[144:147], v[96:99], v[184:187], v[144:147]
	v_mfma_f32_16x16x32_bf16 v[132:135], v[88:91], v[192:195], v[132:135]
	v_mfma_f32_16x16x32_bf16 v[128:131], v[96:99], v[192:195], v[128:131]
	v_mfma_f32_16x16x32_bf16 v[116:119], v[88:91], v[212:215], v[116:119]
	v_mfma_f32_16x16x32_bf16 v[112:115], v[96:99], v[212:215], v[112:115]
	v_mfma_f32_16x16x32_bf16 v[156:159], v[92:95], v[180:183], v[156:159]
	v_mfma_f32_16x16x32_bf16 v[152:155], v[100:103], v[180:183], v[152:155]
	v_mfma_f32_16x16x32_bf16 v[148:151], v[92:95], v[188:191], v[148:151]
	v_mfma_f32_16x16x32_bf16 v[144:147], v[100:103], v[188:191], v[144:147]
	v_mfma_f32_16x16x32_bf16 v[132:135], v[92:95], v[196:199], v[132:135]
	v_mfma_f32_16x16x32_bf16 v[128:131], v[100:103], v[196:199], v[128:131]
	v_mfma_f32_16x16x32_bf16 v[116:119], v[92:95], v[216:219], v[116:119]
	v_mfma_f32_16x16x32_bf16 v[112:115], v[100:103], v[216:219], v[112:115]
	s_setprio 0
	s_barrier
; #define PG8_STAGE(bufoff, gbase, voff) do { _Pragma("unroll") for (int _i = 0; _i < 2; ++_i) \
;         __builtin_amdgcn_global_load_lds((const unsigned*)((const char*)(gbase) + (voff)[_i]), (PG8_LAS unsigned*)(lds + (bufoff) + ldsw + _i * 8192), 16, 0, 0); } while (0)
; #define PG8_LDA(dst, b, h) do { _Pragma("unroll") for (int m = 0; m < 4; ++m) _Pragma("unroll") for (int k = 0; k < 2; ++k) dst[m][k] = *(const PG8_LAS bf16x8*)(lds + PG8_SA(b, h) + aoff + m * 2048 + k * 1024); } while (0)
; #define PG8_MMA(ai, bj, At, Bt) do { __builtin_amdgcn_s_setprio(1); _Pragma("unroll") for (int m = 0; m < 4; ++m) _Pragma("unroll") for (int n = 0; n < 2; ++n) _Pragma("unroll") for (int k = 0; k < 2; ++k) \
;         acc[ai][bj][m][n] = __builtin_amdgcn_mfma_f32_16x16x32_bf16(Bt[n][k], At[m][k], acc[ai][bj][m][n], 0, 0, 0); __builtin_amdgcn_s_setprio(0); } while (0)
; #define PG8_WAIT_V(n) asm volatile("s_waitcnt vmcnt(" #n ")" ::: "memory")
; #define PG8_WAIT_L(n) asm volatile("s_waitcnt lgkmcnt(" #n ")" ::: "memory")
; #define PG8_BAR __builtin_amdgcn_s_barrier()
; #define PG8_SCHED __builtin_amdgcn_sched_barrier(0)
; template <class Epi, class Sched, bool ALIGN_EPI = false, bool SP2 = false, bool AROWS128 = false>
; __device__ __forceinline__ void gemm_phase(PG8_LAS unsigned char* lds, const Gemm g, const Sched& S, const Epi& E) {
;     ...
;         for (int t = 0; t < nt; t += 2) {
;     ...
;             PG8_LDA(At, 1, 1); PG8_STAGE(PG8_SB(1, 0), b3, voffB); PG8_STAGE(PG8_SB(1, 1), b3 + hstep, voffB); PG8_STAGE(PG8_SA(1, 0), a3, voffA);
;             PG8_WAIT_V(8); PG8_WAIT_L(0); PG8_BAR; PG8_MMA(1, 0, At, B0); PG8_MMA(1, 1, At, B1); PG8_BAR; PG8_SCHED;
	s_add_i32 s76, s82, s35
	v_lshl_add_u64 v[220:221], v[220:221], 0, s[26:27]
	s_mov_b32 m0, s76
	ds_read_b128 v[176:179], v209 offset:49152
	ds_read_b128 v[180:183], v209 offset:50176
	ds_read_b128 v[184:187], v209 offset:51200
	ds_read_b128 v[188:191], v209 offset:52224
	ds_read_b128 v[192:195], v209 offset:53248
	ds_read_b128 v[196:199], v209 offset:54272
	ds_read_b128 v[212:215], v209 offset:55296
	ds_read_b128 v[216:219], v209 offset:56320
	global_load_lds_dwordx4 v[220:221], off
	s_add_i32 m0, s76, 0x2000
	s_add_u32 s20, s20, 0x40080
	v_lshl_add_u64 v[220:221], v[222:223], 0, s[26:27]
	s_addc_u32 s21, s21, 0
	s_add_i32 s76, s83, s35
	global_load_lds_dwordx4 v[220:221], off
	v_lshl_add_u64 v[220:221], s[20:21], 0, v[162:163]
	s_mov_b32 m0, s76
	s_nop 0
	global_load_lds_dwordx4 v[220:221], off
	v_lshl_add_u64 v[220:221], s[20:21], 0, v[166:167]
	s_add_i32 m0, s76, 0x2000
	s_nop 0
	global_load_lds_dwordx4 v[220:221], off
	v_lshl_add_u64 v[220:221], v[224:225], 0, s[26:27]
	s_mov_b32 m0, s89
	s_nop 0
	global_load_lds_dwordx4 v[220:221], off
	v_lshl_add_u64 v[220:221], v[226:227], 0, s[26:27]
	s_mov_b32 m0, s90
	s_nop 0
	global_load_lds_dwordx4 v[220:221], off
	s_waitcnt vmcnt(8)
	s_waitcnt lgkmcnt(0)
	s_barrier
	s_setprio 1
	s_waitcnt lgkmcnt(0)
	v_mfma_f32_16x16x32_bf16 v[60:63], v[72:75], v[176:179], v[60:63]
	v_mfma_f32_16x16x32_bf16 v[56:59], v[80:83], v[176:179], v[56:59]
	v_mfma_f32_16x16x32_bf16 v[44:47], v[72:75], v[184:187], v[44:47]
	v_mfma_f32_16x16x32_bf16 v[40:43], v[80:83], v[184:187], v[40:43]
	v_mfma_f32_16x16x32_bf16 v[20:23], v[72:75], v[192:195], v[20:23]
	v_mfma_f32_16x16x32_bf16 v[16:19], v[80:83], v[192:195], v[16:19]
	v_mfma_f32_16x16x32_bf16 v[12:15], v[72:75], v[212:215], v[12:15]
	v_mfma_f32_16x16x32_bf16 v[8:11], v[80:83], v[212:215], v[8:11]
	v_mfma_f32_16x16x32_bf16 v[60:63], v[76:79], v[180:183], v[60:63]
	v_mfma_f32_16x16x32_bf16 v[56:59], v[84:87], v[180:183], v[56:59]
	v_mfma_f32_16x16x32_bf16 v[44:47], v[76:79], v[188:191], v[44:47]
	v_mfma_f32_16x16x32_bf16 v[40:43], v[84:87], v[188:191], v[40:43]
	v_mfma_f32_16x16x32_bf16 v[20:23], v[76:79], v[196:199], v[20:23]
	v_mfma_f32_16x16x32_bf16 v[16:19], v[84:87], v[196:199], v[16:19]
	v_mfma_f32_16x16x32_bf16 v[12:15], v[76:79], v[216:219], v[12:15]
	v_mfma_f32_16x16x32_bf16 v[8:11], v[84:87], v[216:219], v[8:11]
	s_setprio 0
	s_setprio 1
	v_mfma_f32_16x16x32_bf16 v[68:71], v[88:91], v[176:179], v[68:71]
	v_mfma_f32_16x16x32_bf16 v[64:67], v[96:99], v[176:179], v[64:67]
	v_mfma_f32_16x16x32_bf16 v[52:55], v[88:91], v[184:187], v[52:55]
	v_mfma_f32_16x16x32_bf16 v[48:51], v[96:99], v[184:187], v[48:51]
	v_mfma_f32_16x16x32_bf16 v[32:35], v[88:91], v[192:195], v[32:35]
	v_mfma_f32_16x16x32_bf16 v[24:27], v[96:99], v[192:195], v[24:27]
	v_mfma_f32_16x16x32_bf16 v[4:7], v[88:91], v[212:215], v[4:7]
	v_mfma_f32_16x16x32_bf16 v[0:3], v[96:99], v[212:215], v[0:3]
	v_mfma_f32_16x16x32_bf16 v[68:71], v[92:95], v[180:183], v[68:71]
	v_mfma_f32_16x16x32_bf16 v[64:67], v[100:103], v[180:183], v[64:67]
	v_mfma_f32_16x16x32_bf16 v[52:55], v[92:95], v[188:191], v[52:55]
	v_mfma_f32_16x16x32_bf16 v[48:51], v[100:103], v[188:191], v[48:51]
	v_mfma_f32_16x16x32_bf16 v[32:35], v[92:95], v[196:199], v[32:35]
	v_mfma_f32_16x16x32_bf16 v[24:27], v[100:103], v[196:199], v[24:27]
	v_mfma_f32_16x16x32_bf16 v[4:7], v[92:95], v[216:219], v[4:7]
	v_mfma_f32_16x16x32_bf16 v[0:3], v[100:103], v[216:219], v[0:3]
	s_setprio 0
	s_add_i32 s73, s73, 2
	s_add_u32 s18, s18, 0x100
	s_addc_u32 s19, s19, 0
	s_add_u32 s65, s65, 0x100
	s_addc_u32 s72, s72, 0
	s_cmp_gt_u32 s73, 13
	s_cbranch_scc0 .Lrot_k2
	s_barrier
	s_and_b64 vcc, exec, s[28:29]
	s_cbranch_vccz .LBB0_629
	s_barrier

; template <class Epi, class Sched, bool ALIGN_EPI = false, bool SP2 = false, bool AROWS128 = false>
; __device__ __forceinline__ void gemm_phase(PG8_LAS unsigned char* lds, const Gemm g, const Sched& S, const Epi& E) {
;     ...
;         const bool has_next = S.next(ui + 1, nxt);
;         const char* nA = has_next ? (const char*)g.A + (size_t)nxt.pm * tstep : cA; const char* nB = has_next ? (const char*)g.Bt + (size_t)nxt.pn * tstep : cB;
;     ...
; #pragma unroll
;         for (int a = 0; a < 2; ++a)
; #pragma unroll
;             for (int b = 0; b < 2; ++b)
; #pragma unroll
;                 for (int m = 0; m < 4; ++m)
; #pragma unroll
;                     for (int n = 0; n < 2; ++n) acc[a][b][m][n] = (f32x4){0.f, 0.f, 0.f, 0.f};
.LBB0_751:
	s_ashr_i32 s25, s24, 31
	s_lshl_b64 s[26:27], s[24:25], 21
	s_add_u32 s26, s44, s26
	s_addc_u32 s27, s45, s27
	s_and_b64 s[28:29], s[0:1], exec
	s_cselect_b32 s25, s27, s37
	s_cselect_b32 s65, s26, s36
	s_ashr_i32 s21, s20, 31
	s_lshl_b64 s[28:29], s[20:21], 21
	v_readlane_b32 s48, v255, 13
	v_readlane_b32 s49, v255, 14
	s_add_u32 s28, s48, s28
	s_addc_u32 s29, s49, s29
	s_and_b64 s[48:49], s[0:1], exec
	s_cselect_b32 s21, s29, s39
	s_cselect_b32 s72, s28, s38
	s_add_u32 s36, s36, 0x100080
	s_addc_u32 s37, s37, 0
	s_add_u32 s73, s38, 0x100
	v_mov_b32_e32 v0, 0
	s_addc_u32 s76, s39, 0
	s_mov_b32 s77, -2
	v_mov_b64_e32 v[0:1], 0
	v_mov_b64_e32 v[2:3], 0
	v_mov_b64_e32 v[4:5], 0
	v_mov_b64_e32 v[6:7], 0
	v_mov_b64_e32 v[8:9], 0
	v_mov_b64_e32 v[10:11], 0
	v_mov_b64_e32 v[12:13], 0
	v_mov_b64_e32 v[14:15], 0
	v_mov_b64_e32 v[16:17], 0
	v_mov_b64_e32 v[18:19], 0
	v_mov_b64_e32 v[20:21], 0
	v_mov_b64_e32 v[22:23], 0
	v_mov_b64_e32 v[24:25], 0
	v_mov_b64_e32 v[26:27], 0
	v_mov_b64_e32 v[28:29], 0
	v_mov_b64_e32 v[30:31], 0
	v_mov_b64_e32 v[32:33], 0
	v_mov_b64_e32 v[34:35], 0
	v_mov_b64_e32 v[36:37], 0
	v_mov_b64_e32 v[38:39], 0
	v_mov_b64_e32 v[40:41], 0
	v_mov_b64_e32 v[42:43], 0
	v_mov_b64_e32 v[44:45], 0
	v_mov_b64_e32 v[46:47], 0
	v_mov_b64_e32 v[48:49], 0
	v_mov_b64_e32 v[50:51], 0
	v_mov_b64_e32 v[52:53], 0
	v_mov_b64_e32 v[54:55], 0
	v_mov_b64_e32 v[56:57], 0
	v_mov_b64_e32 v[58:59], 0
	v_mov_b64_e32 v[60:61], 0
	v_mov_b64_e32 v[62:63], 0
	v_mov_b64_e32 v[64:65], 0
	v_mov_b64_e32 v[66:67], 0
	v_mov_b64_e32 v[68:69], 0
	v_mov_b64_e32 v[70:71], 0
	v_mov_b64_e32 v[72:73], 0
	v_mov_b64_e32 v[74:75], 0
	v_mov_b64_e32 v[76:77], 0
	v_mov_b64_e32 v[78:79], 0
	v_mov_b64_e32 v[80:81], 0
	v_mov_b64_e32 v[82:83], 0
	v_mov_b64_e32 v[84:85], 0
	v_mov_b64_e32 v[86:87], 0
	v_mov_b64_e32 v[88:89], 0
	v_mov_b64_e32 v[90:91], 0
	v_mov_b64_e32 v[92:93], 0
	v_mov_b64_e32 v[94:95], 0
	v_mov_b64_e32 v[96:97], 0
	v_mov_b64_e32 v[98:99], 0
	v_mov_b64_e32 v[100:101], 0
	v_mov_b64_e32 v[102:103], 0
	v_mov_b64_e32 v[104:105], 0
	v_mov_b64_e32 v[106:107], 0
	v_mov_b64_e32 v[108:109], 0
	v_mov_b64_e32 v[110:111], 0
	v_mov_b64_e32 v[112:113], 0
	v_mov_b64_e32 v[114:115], 0
	v_mov_b64_e32 v[116:117], 0
	v_mov_b64_e32 v[118:119], 0
	v_mov_b64_e32 v[120:121], 0
	v_mov_b64_e32 v[122:123], 0
	v_mov_b64_e32 v[124:125], 0
	v_mov_b64_e32 v[126:127], 0
	s_branch .LBB0_752

; #define PG8_STAGE(bufoff, gbase, voff) do { _Pragma("unroll") for (int _i = 0; _i < 2; ++_i) \
;         __builtin_amdgcn_global_load_lds((const unsigned*)((const char*)(gbase) + (voff)[_i]), (PG8_LAS unsigned*)(lds + (bufoff) + ldsw + _i * 8192), 16, 0, 0); } while (0)
; #define PG8_LDA(dst, b, h) do { _Pragma("unroll") for (int m = 0; m < 4; ++m) _Pragma("unroll") for (int k = 0; k < 2; ++k) dst[m][k] = *(const PG8_LAS bf16x8*)(lds + PG8_SA(b, h) + aoff + m * 2048 + k * 1024); } while (0)
; #define PG8_LDB(dst, b, h) do { _Pragma("unroll") for (int n = 0; n < 2; ++n) _Pragma("unroll") for (int k = 0; k < 2; ++k) dst[n][k] = *(const PG8_LAS bf16x8*)(lds + PG8_SB(b, h) + boff + n * 2048 + k * 1024); } while (0)
; #define PG8_MMA(ai, bj, At, Bt) do { __builtin_amdgcn_s_setprio(1); _Pragma("unroll") for (int m = 0; m < 4; ++m) _Pragma("unroll") for (int n = 0; n < 2; ++n) _Pragma("unroll") for (int k = 0; k < 2; ++k) \
;         acc[ai][bj][m][n] = __builtin_amdgcn_mfma_f32_16x16x32_bf16(Bt[n][k], At[m][k], acc[ai][bj][m][n], 0, 0, 0); __builtin_amdgcn_s_setprio(0); } while (0)
; #define PG8_WAIT_V(n) asm volatile("s_waitcnt vmcnt(" #n ")" ::: "memory")
; #define PG8_WAIT_L(n) asm volatile("s_waitcnt lgkmcnt(" #n ")" ::: "memory")
; #define PG8_BAR __builtin_amdgcn_s_barrier()
; #define PG8_SCHED __builtin_amdgcn_sched_barrier(0)
; template <class Epi, class Sched, bool ALIGN_EPI = false, bool SP2 = false, bool AROWS128 = false>
; __device__ __forceinline__ void gemm_phase(PG8_LAS unsigned char* lds, const Gemm g, const Sched& S, const Epi& E) {
;     ...
;             PG8_LDB(B0, 0, 0); PG8_LDB(B1, 0, 1); PG8_SCHED; PG8_LDA(At, 0, 0); PG8_STAGE(PG8_SA(1, 1), a1 + hstepA, voffA);
;             PG8_WAIT_V(8); PG8_WAIT_L(0); PG8_BAR; PG8_MMA(0, 0, At, B0); PG8_MMA(0, 1, At, B1); PG8_BAR; PG8_SCHED;
;             PG8_LDA(At, 0, 1); PG8_STAGE(PG8_SB(0, 0), b2, voffB); PG8_STAGE(PG8_SB(0, 1), b2 + hstep, voffB); PG8_STAGE(PG8_SA(0, 0), a2, voffA);
;             PG8_WAIT_V(8); PG8_WAIT_L(0); PG8_BAR; PG8_MMA(1, 0, At, B0); PG8_MMA(1, 1, At, B1); PG8_BAR; PG8_SCHED;
;             PG8_LDB(B0, 1, 0); PG8_LDB(B1, 1, 1); PG8_SCHED; PG8_LDA(At, 1, 0); PG8_STAGE(PG8_SA(0, 1), a2 + hstepA, voffA);
;             PG8_WAIT_V(8); PG8_WAIT_L(0); PG8_BAR; PG8_MMA(0, 0, At, B0); PG8_MMA(0, 1, At, B1); PG8_BAR; PG8_SCHED;
.LBB0_752:
	ds_read_b128 v[152:155], v149
	ds_read_b128 v[156:159], v149 offset:1024
	ds_read_b128 v[160:163], v149 offset:2048
	ds_read_b128 v[164:167], v149 offset:3072
	ds_read_b128 v[168:171], v150
	ds_read_b128 v[172:175], v150 offset:1024
	ds_read_b128 v[176:179], v150 offset:2048
	ds_read_b128 v[180:183], v150 offset:3072
	s_add_u32 s38, s36, 0xfff00080
	s_addc_u32 s39, s37, -1
	s_cmp_eq_u32 s77, 60
	s_cselect_b32 s49, s25, s39
	s_cselect_b32 s48, s65, s38
	s_cselect_b32 s39, s21, s76
	s_cselect_b32 s38, s72, s73
	v_lshl_add_u64 v[144:145], s[36:37], 0, v[136:137]
	s_add_i32 m0, s31, 0xc000
	ds_read_b128 v[184:187], v151
	ds_read_b128 v[188:191], v151 offset:1024
	ds_read_b128 v[192:195], v151 offset:2048
	ds_read_b128 v[196:199], v151 offset:3072
	ds_read_b128 v[200:203], v151 offset:4096
	ds_read_b128 v[204:207], v151 offset:5120
	ds_read_b128 v[212:215], v151 offset:6144
	ds_read_b128 v[216:219], v151 offset:7168
	global_load_lds_dwordx4 v[144:145], off
	v_lshl_add_u64 v[144:145], s[36:37], 0, v[138:139]
	s_add_i32 m0, s31, 0xe000
	s_nop 0
	global_load_lds_dwordx4 v[144:145], off
	s_waitcnt vmcnt(8)
	s_waitcnt lgkmcnt(0)
	s_barrier
	s_setprio 1
	s_waitcnt lgkmcnt(0)
	v_mfma_f32_16x16x32_bf16 v[124:127], v[152:155], v[184:187], v[124:127]
	v_mfma_f32_16x16x32_bf16 v[120:123], v[160:163], v[184:187], v[120:123]
	v_mfma_f32_16x16x32_bf16 v[116:119], v[152:155], v[192:195], v[116:119]
	v_mfma_f32_16x16x32_bf16 v[108:111], v[160:163], v[192:195], v[108:111]
	v_mfma_f32_16x16x32_bf16 v[100:103], v[152:155], v[200:203], v[100:103]
	v_mfma_f32_16x16x32_bf16 v[92:95], v[160:163], v[200:203], v[92:95]
	v_mfma_f32_16x16x32_bf16 v[84:87], v[152:155], v[212:215], v[84:87]
	v_mfma_f32_16x16x32_bf16 v[76:79], v[160:163], v[212:215], v[76:79]
	v_mfma_f32_16x16x32_bf16 v[124:127], v[156:159], v[188:191], v[124:127]
	v_mfma_f32_16x16x32_bf16 v[120:123], v[164:167], v[188:191], v[120:123]
	v_mfma_f32_16x16x32_bf16 v[116:119], v[156:159], v[196:199], v[116:119]
	v_mfma_f32_16x16x32_bf16 v[108:111], v[164:167], v[196:199], v[108:111]
	v_mfma_f32_16x16x32_bf16 v[100:103], v[156:159], v[204:207], v[100:103]
	v_mfma_f32_16x16x32_bf16 v[92:95], v[164:167], v[204:207], v[92:95]
	v_mfma_f32_16x16x32_bf16 v[84:87], v[156:159], v[216:219], v[84:87]
	v_mfma_f32_16x16x32_bf16 v[76:79], v[164:167], v[216:219], v[76:79]
	s_setprio 0
	s_setprio 1
	v_mfma_f32_16x16x32_bf16 v[112:115], v[168:171], v[184:187], v[112:115]
	v_mfma_f32_16x16x32_bf16 v[104:107], v[176:179], v[184:187], v[104:107]
	v_mfma_f32_16x16x32_bf16 v[96:99], v[168:171], v[192:195], v[96:99]
	v_mfma_f32_16x16x32_bf16 v[88:91], v[176:179], v[192:195], v[88:91]
	v_mfma_f32_16x16x32_bf16 v[80:83], v[168:171], v[200:203], v[80:83]
	v_mfma_f32_16x16x32_bf16 v[72:75], v[176:179], v[200:203], v[72:75]
	v_mfma_f32_16x16x32_bf16 v[68:71], v[168:171], v[212:215], v[68:71]
	v_mfma_f32_16x16x32_bf16 v[64:67], v[176:179], v[212:215], v[64:67]
	v_mfma_f32_16x16x32_bf16 v[112:115], v[172:175], v[188:191], v[112:115]
	v_mfma_f32_16x16x32_bf16 v[104:107], v[180:183], v[188:191], v[104:107]
	v_mfma_f32_16x16x32_bf16 v[96:99], v[172:175], v[196:199], v[96:99]
	v_mfma_f32_16x16x32_bf16 v[88:91], v[180:183], v[196:199], v[88:91]
	v_mfma_f32_16x16x32_bf16 v[80:83], v[172:175], v[204:207], v[80:83]
	v_mfma_f32_16x16x32_bf16 v[72:75], v[180:183], v[204:207], v[72:75]
	v_mfma_f32_16x16x32_bf16 v[68:71], v[172:175], v[216:219], v[68:71]
	v_mfma_f32_16x16x32_bf16 v[64:67], v[180:183], v[216:219], v[64:67]
	s_setprio 0
	s_barrier
	s_add_i32 s78, s58, s3
	v_lshl_add_u64 v[144:145], s[38:39], 0, v[132:133]
	s_mov_b32 m0, s78
	ds_read_b128 v[184:187], v151 offset:16384
	ds_read_b128 v[188:191], v151 offset:17408
	ds_read_b128 v[192:195], v151 offset:18432
	ds_read_b128 v[196:199], v151 offset:19456
	ds_read_b128 v[200:203], v151 offset:20480
	ds_read_b128 v[204:207], v151 offset:21504
	ds_read_b128 v[212:215], v151 offset:22528
	ds_read_b128 v[216:219], v151 offset:23552
	global_load_lds_dwordx4 v[144:145], off
	s_add_i32 m0, s78, 0x2000
	s_add_u32 s78, s38, 0x100000
	v_lshl_add_u64 v[208:209], s[38:39], 0, v[128:129]
	s_addc_u32 s79, s39, 0
	s_add_i32 s80, s59, s3
	global_load_lds_dwordx4 v[208:209], off
	v_lshl_add_u64 v[220:221], s[78:79], 0, v[132:133]
	s_mov_b32 m0, s80
	v_lshl_add_u64 v[222:223], s[48:49], 0, v[130:131]
	global_load_lds_dwordx4 v[220:221], off
	v_lshl_add_u64 v[220:221], s[78:79], 0, v[128:129]
	s_add_i32 m0, s80, 0x2000
	s_nop 0
	global_load_lds_dwordx4 v[220:221], off
	v_lshl_add_u64 v[220:221], s[48:49], 0, v[134:135]
	s_mov_b32 m0, s31
	s_nop 0
	global_load_lds_dwordx4 v[220:221], off
	s_mov_b32 m0, s50
	s_nop 0
	global_load_lds_dwordx4 v[222:223], off
	s_waitcnt vmcnt(8)
	s_waitcnt lgkmcnt(0)
	s_barrier
; #define PG8_STAGE(bufoff, gbase, voff) do { _Pragma("unroll") for (int _i = 0; _i < 2; ++_i) \
;         __builtin_amdgcn_global_load_lds((const unsigned*)((const char*)(gbase) + (voff)[_i]), (PG8_LAS unsigned*)(lds + (bufoff) + ldsw + _i * 8192), 16, 0, 0); } while (0)
; #define PG8_LDA(dst, b, h) do { _Pragma("unroll") for (int m = 0; m < 4; ++m) _Pragma("unroll") for (int k = 0; k < 2; ++k) dst[m][k] = *(const PG8_LAS bf16x8*)(lds + PG8_SA(b, h) + aoff + m * 2048 + k * 1024); } while (0)
; #define PG8_LDB(dst, b, h) do { _Pragma("unroll") for (int n = 0; n < 2; ++n) _Pragma("unroll") for (int k = 0; k < 2; ++k) dst[n][k] = *(const PG8_LAS bf16x8*)(lds + PG8_SB(b, h) + boff + n * 2048 + k * 1024); } while (0)
; #define PG8_MMA(ai, bj, At, Bt) do { __builtin_amdgcn_s_setprio(1); _Pragma("unroll") for (int m = 0; m < 4; ++m) _Pragma("unroll") for (int n = 0; n < 2; ++n) _Pragma("unroll") for (int k = 0; k < 2; ++k) \
;         acc[ai][bj][m][n] = __builtin_amdgcn_mfma_f32_16x16x32_bf16(Bt[n][k], At[m][k], acc[ai][bj][m][n], 0, 0, 0); __builtin_amdgcn_s_setprio(0); } while (0)
; #define PG8_WAIT_V(n) asm volatile("s_waitcnt vmcnt(" #n ")" ::: "memory")
; #define PG8_WAIT_L(n) asm volatile("s_waitcnt lgkmcnt(" #n ")" ::: "memory")
; #define PG8_BAR __builtin_amdgcn_s_barrier()
; #define PG8_SCHED __builtin_amdgcn_sched_barrier(0)
; template <class Epi, class Sched, bool ALIGN_EPI = false, bool SP2 = false, bool AROWS128 = false>
; __device__ __forceinline__ void gemm_phase(PG8_LAS unsigned char* lds, const Gemm g, const Sched& S, const Epi& E) {
;     ...
;             PG8_WAIT_V(8); PG8_WAIT_L(0); PG8_BAR; PG8_MMA(1, 0, At, B0); PG8_MMA(1, 1, At, B1); PG8_BAR; PG8_SCHED;
;             PG8_LDB(B0, 1, 0); PG8_LDB(B1, 1, 1); PG8_SCHED; PG8_LDA(At, 1, 0); PG8_STAGE(PG8_SA(0, 1), a2 + hstepA, voffA);
;             PG8_WAIT_V(8); PG8_WAIT_L(0); PG8_BAR; PG8_MMA(0, 0, At, B0); PG8_MMA(0, 1, At, B1); PG8_BAR; PG8_SCHED;
	s_setprio 1
	s_waitcnt lgkmcnt(0)
	v_mfma_f32_16x16x32_bf16 v[60:63], v[152:155], v[184:187], v[60:63]
	v_mfma_f32_16x16x32_bf16 v[56:59], v[160:163], v[184:187], v[56:59]
	v_mfma_f32_16x16x32_bf16 v[52:55], v[152:155], v[192:195], v[52:55]
	v_mfma_f32_16x16x32_bf16 v[44:47], v[160:163], v[192:195], v[44:47]
	v_mfma_f32_16x16x32_bf16 v[36:39], v[152:155], v[200:203], v[36:39]
	v_mfma_f32_16x16x32_bf16 v[28:31], v[160:163], v[200:203], v[28:31]
	v_mfma_f32_16x16x32_bf16 v[20:23], v[152:155], v[212:215], v[20:23]
	v_mfma_f32_16x16x32_bf16 v[12:15], v[160:163], v[212:215], v[12:15]
	v_mfma_f32_16x16x32_bf16 v[60:63], v[156:159], v[188:191], v[60:63]
	v_mfma_f32_16x16x32_bf16 v[56:59], v[164:167], v[188:191], v[56:59]
	v_mfma_f32_16x16x32_bf16 v[52:55], v[156:159], v[196:199], v[52:55]
	v_mfma_f32_16x16x32_bf16 v[44:47], v[164:167], v[196:199], v[44:47]
	v_mfma_f32_16x16x32_bf16 v[36:39], v[156:159], v[204:207], v[36:39]
	v_mfma_f32_16x16x32_bf16 v[28:31], v[164:167], v[204:207], v[28:31]
	v_mfma_f32_16x16x32_bf16 v[20:23], v[156:159], v[216:219], v[20:23]
	v_mfma_f32_16x16x32_bf16 v[12:15], v[164:167], v[216:219], v[12:15]
	s_setprio 0
	s_setprio 1
	v_mfma_f32_16x16x32_bf16 v[48:51], v[168:171], v[184:187], v[48:51]
	v_mfma_f32_16x16x32_bf16 v[40:43], v[176:179], v[184:187], v[40:43]
	v_mfma_f32_16x16x32_bf16 v[32:35], v[168:171], v[192:195], v[32:35]
	v_mfma_f32_16x16x32_bf16 v[24:27], v[176:179], v[192:195], v[24:27]
	v_mfma_f32_16x16x32_bf16 v[16:19], v[168:171], v[200:203], v[16:19]
	v_mfma_f32_16x16x32_bf16 v[8:11], v[176:179], v[200:203], v[8:11]
	v_mfma_f32_16x16x32_bf16 v[4:7], v[168:171], v[212:215], v[4:7]
	v_mfma_f32_16x16x32_bf16 v[0:3], v[176:179], v[212:215], v[0:3]
	v_mfma_f32_16x16x32_bf16 v[48:51], v[172:175], v[188:191], v[48:51]
	v_mfma_f32_16x16x32_bf16 v[40:43], v[180:183], v[188:191], v[40:43]
	v_mfma_f32_16x16x32_bf16 v[32:35], v[172:175], v[196:199], v[32:35]
	v_mfma_f32_16x16x32_bf16 v[24:27], v[180:183], v[196:199], v[24:27]
	v_mfma_f32_16x16x32_bf16 v[16:19], v[172:175], v[204:207], v[16:19]
	v_mfma_f32_16x16x32_bf16 v[8:11], v[180:183], v[204:207], v[8:11]
	v_mfma_f32_16x16x32_bf16 v[4:7], v[172:175], v[216:219], v[4:7]
	v_mfma_f32_16x16x32_bf16 v[0:3], v[180:183], v[216:219], v[0:3]
	s_setprio 0
	s_barrier
	s_add_i32 s78, 0, 0x18000
	s_add_i32 s79, 0, 0x1c000
	v_add_u32_e32 v164, s78, v147
	v_add_u32_e32 v180, s79, v147
	ds_read_b128 v[152:155], v164
	ds_read_b128 v[156:159], v164 offset:1024
	ds_read_b128 v[160:163], v164 offset:2048
	ds_read_b128 v[164:167], v164 offset:3072
	ds_read_b128 v[168:171], v180
	ds_read_b128 v[172:175], v180 offset:1024
	ds_read_b128 v[176:179], v180 offset:2048
	ds_read_b128 v[180:183], v180 offset:3072
	s_add_u32 s48, s48, 0x100000
	s_addc_u32 s49, s49, 0
	s_mov_b32 m0, s51
	v_lshl_add_u64 v[224:225], s[48:49], 0, v[134:135]
	ds_read_b128 v[184:187], v151 offset:32768
	ds_read_b128 v[188:191], v151 offset:33792
	ds_read_b128 v[192:195], v151 offset:34816
	ds_read_b128 v[196:199], v151 offset:35840
	ds_read_b128 v[200:203], v151 offset:36864
	ds_read_b128 v[204:207], v151 offset:37888
	ds_read_b128 v[212:215], v151 offset:38912
	ds_read_b128 v[216:219], v151 offset:39936
	global_load_lds_dwordx4 v[224:225], off
	v_lshl_add_u64 v[224:225], s[48:49], 0, v[130:131]
	s_mov_b32 m0, s52
	s_nop 0
	global_load_lds_dwordx4 v[224:225], off
	s_waitcnt vmcnt(8)
	s_waitcnt lgkmcnt(0)
	s_barrier
	s_setprio 1
	s_waitcnt lgkmcnt(0)
	v_mfma_f32_16x16x32_bf16 v[124:127], v[152:155], v[184:187], v[124:127]
	v_mfma_f32_16x16x32_bf16 v[120:123], v[160:163], v[184:187], v[120:123]
	v_mfma_f32_16x16x32_bf16 v[116:119], v[152:155], v[192:195], v[116:119]
	v_mfma_f32_16x16x32_bf16 v[108:111], v[160:163], v[192:195], v[108:111]
	v_mfma_f32_16x16x32_bf16 v[100:103], v[152:155], v[200:203], v[100:103]
	v_mfma_f32_16x16x32_bf16 v[92:95], v[160:163], v[200:203], v[92:95]
	v_mfma_f32_16x16x32_bf16 v[84:87], v[152:155], v[212:215], v[84:87]
	v_mfma_f32_16x16x32_bf16 v[76:79], v[160:163], v[212:215], v[76:79]
	v_mfma_f32_16x16x32_bf16 v[124:127], v[156:159], v[188:191], v[124:127]
	v_mfma_f32_16x16x32_bf16 v[120:123], v[164:167], v[188:191], v[120:123]
	v_mfma_f32_16x16x32_bf16 v[116:119], v[156:159], v[196:199], v[116:119]
	v_mfma_f32_16x16x32_bf16 v[108:111], v[164:167], v[196:199], v[108:111]
	v_mfma_f32_16x16x32_bf16 v[100:103], v[156:159], v[204:207], v[100:103]
	v_mfma_f32_16x16x32_bf16 v[92:95], v[164:167], v[204:207], v[92:95]
	v_mfma_f32_16x16x32_bf16 v[84:87], v[156:159], v[216:219], v[84:87]
	v_mfma_f32_16x16x32_bf16 v[76:79], v[164:167], v[216:219], v[76:79]
	s_setprio 0
	s_setprio 1
	v_mfma_f32_16x16x32_bf16 v[112:115], v[168:171], v[184:187], v[112:115]
	v_mfma_f32_16x16x32_bf16 v[104:107], v[176:179], v[184:187], v[104:107]
	v_mfma_f32_16x16x32_bf16 v[96:99], v[168:171], v[192:195], v[96:99]
	v_mfma_f32_16x16x32_bf16 v[88:91], v[176:179], v[192:195], v[88:91]
	v_mfma_f32_16x16x32_bf16 v[80:83], v[168:171], v[200:203], v[80:83]
	v_mfma_f32_16x16x32_bf16 v[72:75], v[176:179], v[200:203], v[72:75]
	v_mfma_f32_16x16x32_bf16 v[68:71], v[168:171], v[212:215], v[68:71]
	v_mfma_f32_16x16x32_bf16 v[64:67], v[176:179], v[212:215], v[64:67]
	v_mfma_f32_16x16x32_bf16 v[112:115], v[172:175], v[188:191], v[112:115]
	v_mfma_f32_16x16x32_bf16 v[104:107], v[180:183], v[188:191], v[104:107]
	v_mfma_f32_16x16x32_bf16 v[96:99], v[172:175], v[196:199], v[96:99]
	v_mfma_f32_16x16x32_bf16 v[88:91], v[180:183], v[196:199], v[88:91]
	v_mfma_f32_16x16x32_bf16 v[80:83], v[172:175], v[204:207], v[80:83]
	v_mfma_f32_16x16x32_bf16 v[72:75], v[180:183], v[204:207], v[72:75]
	v_mfma_f32_16x16x32_bf16 v[68:71], v[172:175], v[216:219], v[68:71]
	v_mfma_f32_16x16x32_bf16 v[64:67], v[180:183], v[216:219], v[64:67]
	s_setprio 0
	s_barrier
; #define PG8_STAGE(bufoff, gbase, voff) do { _Pragma("unroll") for (int _i = 0; _i < 2; ++_i) \
;         __builtin_amdgcn_global_load_lds((const unsigned*)((const char*)(gbase) + (voff)[_i]), (PG8_LAS unsigned*)(lds + (bufoff) + ldsw + _i * 8192), 16, 0, 0); } while (0)
; #define PG8_LDA(dst, b, h) do { _Pragma("unroll") for (int m = 0; m < 4; ++m) _Pragma("unroll") for (int k = 0; k < 2; ++k) dst[m][k] = *(const PG8_LAS bf16x8*)(lds + PG8_SA(b, h) + aoff + m * 2048 + k * 1024); } while (0)
; #define PG8_MMA(ai, bj, At, Bt) do { __builtin_amdgcn_s_setprio(1); _Pragma("unroll") for (int m = 0; m < 4; ++m) _Pragma("unroll") for (int n = 0; n < 2; ++n) _Pragma("unroll") for (int k = 0; k < 2; ++k) \
;         acc[ai][bj][m][n] = __builtin_amdgcn_mfma_f32_16x16x32_bf16(Bt[n][k], At[m][k], acc[ai][bj][m][n], 0, 0, 0); __builtin_amdgcn_s_setprio(0); } while (0)
; #define PG8_WAIT_V(n) asm volatile("s_waitcnt vmcnt(" #n ")" ::: "memory")
; #define PG8_WAIT_L(n) asm volatile("s_waitcnt lgkmcnt(" #n ")" ::: "memory")
; #define PG8_BAR __builtin_amdgcn_s_barrier()
; #define PG8_SCHED __builtin_amdgcn_sched_barrier(0)
; template <class Epi, class Sched, bool ALIGN_EPI = false, bool SP2 = false, bool AROWS128 = false>
; __device__ __forceinline__ void gemm_phase(PG8_LAS unsigned char* lds, const Gemm g, const Sched& S, const Epi& E) {
;     ...
;         for (int t = 0; t < nt; t += 2) {
;     ...
;             PG8_LDA(At, 1, 1); PG8_STAGE(PG8_SB(1, 0), b3, voffB); PG8_STAGE(PG8_SB(1, 1), b3 + hstep, voffB); PG8_STAGE(PG8_SA(1, 0), a3, voffA);
;             PG8_WAIT_V(8); PG8_WAIT_L(0); PG8_BAR; PG8_MMA(1, 0, At, B0); PG8_MMA(1, 1, At, B1); PG8_BAR; PG8_SCHED;
	s_add_i32 s48, s78, s3
	v_lshl_add_u64 v[144:145], v[144:145], 0, s[8:9]
	s_mov_b32 m0, s48
	ds_read_b128 v[184:187], v151 offset:49152
	ds_read_b128 v[188:191], v151 offset:50176
	ds_read_b128 v[192:195], v151 offset:51200
	ds_read_b128 v[196:199], v151 offset:52224
	ds_read_b128 v[200:203], v151 offset:53248
	ds_read_b128 v[204:207], v151 offset:54272
	ds_read_b128 v[212:215], v151 offset:55296
	ds_read_b128 v[216:219], v151 offset:56320
	global_load_lds_dwordx4 v[144:145], off
	s_add_i32 m0, s48, 0x2000
	s_add_u32 s38, s38, 0x100080
	v_lshl_add_u64 v[144:145], v[208:209], 0, s[8:9]
	s_addc_u32 s39, s39, 0
	s_add_i32 s48, s79, s3
	global_load_lds_dwordx4 v[144:145], off
	v_lshl_add_u64 v[144:145], s[38:39], 0, v[132:133]
	s_mov_b32 m0, s48
	s_nop 0
	global_load_lds_dwordx4 v[144:145], off
	v_lshl_add_u64 v[144:145], s[38:39], 0, v[128:129]
	s_add_i32 m0, s48, 0x2000
	s_nop 0
	global_load_lds_dwordx4 v[144:145], off
	v_lshl_add_u64 v[144:145], v[220:221], 0, s[8:9]
	s_mov_b32 m0, s54
	s_nop 0
	global_load_lds_dwordx4 v[144:145], off
	v_lshl_add_u64 v[144:145], v[222:223], 0, s[8:9]
	s_mov_b32 m0, s55
	s_nop 0
	global_load_lds_dwordx4 v[144:145], off
	s_waitcnt vmcnt(8)
	s_waitcnt lgkmcnt(0)
	s_barrier
	s_setprio 1
	s_waitcnt lgkmcnt(0)
	v_mfma_f32_16x16x32_bf16 v[60:63], v[152:155], v[184:187], v[60:63]
	v_mfma_f32_16x16x32_bf16 v[56:59], v[160:163], v[184:187], v[56:59]
	v_mfma_f32_16x16x32_bf16 v[52:55], v[152:155], v[192:195], v[52:55]
	v_mfma_f32_16x16x32_bf16 v[44:47], v[160:163], v[192:195], v[44:47]
	v_mfma_f32_16x16x32_bf16 v[36:39], v[152:155], v[200:203], v[36:39]
	v_mfma_f32_16x16x32_bf16 v[28:31], v[160:163], v[200:203], v[28:31]
	v_mfma_f32_16x16x32_bf16 v[20:23], v[152:155], v[212:215], v[20:23]
	v_mfma_f32_16x16x32_bf16 v[12:15], v[160:163], v[212:215], v[12:15]
	v_mfma_f32_16x16x32_bf16 v[60:63], v[156:159], v[188:191], v[60:63]
	v_mfma_f32_16x16x32_bf16 v[56:59], v[164:167], v[188:191], v[56:59]
	v_mfma_f32_16x16x32_bf16 v[52:55], v[156:159], v[196:199], v[52:55]
	v_mfma_f32_16x16x32_bf16 v[44:47], v[164:167], v[196:199], v[44:47]
	v_mfma_f32_16x16x32_bf16 v[36:39], v[156:159], v[204:207], v[36:39]
	v_mfma_f32_16x16x32_bf16 v[28:31], v[164:167], v[204:207], v[28:31]
	v_mfma_f32_16x16x32_bf16 v[20:23], v[156:159], v[216:219], v[20:23]
	v_mfma_f32_16x16x32_bf16 v[12:15], v[164:167], v[216:219], v[12:15]
	s_setprio 0
	s_setprio 1
	v_mfma_f32_16x16x32_bf16 v[48:51], v[168:171], v[184:187], v[48:51]
	v_mfma_f32_16x16x32_bf16 v[40:43], v[176:179], v[184:187], v[40:43]
	v_mfma_f32_16x16x32_bf16 v[32:35], v[168:171], v[192:195], v[32:35]
	v_mfma_f32_16x16x32_bf16 v[24:27], v[176:179], v[192:195], v[24:27]
	v_mfma_f32_16x16x32_bf16 v[16:19], v[168:171], v[200:203], v[16:19]
	v_mfma_f32_16x16x32_bf16 v[8:11], v[176:179], v[200:203], v[8:11]
	v_mfma_f32_16x16x32_bf16 v[4:7], v[168:171], v[212:215], v[4:7]
	v_mfma_f32_16x16x32_bf16 v[0:3], v[176:179], v[212:215], v[0:3]
	v_mfma_f32_16x16x32_bf16 v[48:51], v[172:175], v[188:191], v[48:51]
	v_mfma_f32_16x16x32_bf16 v[40:43], v[180:183], v[188:191], v[40:43]
	v_mfma_f32_16x16x32_bf16 v[32:35], v[172:175], v[196:199], v[32:35]
	v_mfma_f32_16x16x32_bf16 v[24:27], v[180:183], v[196:199], v[24:27]
	v_mfma_f32_16x16x32_bf16 v[16:19], v[172:175], v[204:207], v[16:19]
	v_mfma_f32_16x16x32_bf16 v[8:11], v[180:183], v[204:207], v[8:11]
	v_mfma_f32_16x16x32_bf16 v[4:7], v[172:175], v[216:219], v[4:7]
	v_mfma_f32_16x16x32_bf16 v[0:3], v[180:183], v[216:219], v[0:3]
	s_setprio 0
	s_add_i32 s77, s77, 2
	s_add_u32 s36, s36, 0x100
	s_addc_u32 s37, s37, 0
	s_add_u32 s73, s73, 0x100
	s_addc_u32 s76, s76, 0
	s_cmp_gt_u32 s77, 61
	s_cbranch_scc0 .Lrot_k3
	s_barrier
	s_and_b64 vcc, exec, s[10:11]
	s_cbranch_vccz .LBB0_755
	s_barrier

; template <class Epi, class Sched, bool ALIGN_EPI = false, bool SP2 = false, bool AROWS128 = false>
; __device__ __forceinline__ void gemm_phase(PG8_LAS unsigned char* lds, const Gemm g, const Sched& S, const Epi& E) {
;     ...
;         const bool has_next = S.next(ui + 1, nxt);
;         const char* nA = has_next ? (const char*)g.A + (size_t)nxt.pm * tstep : cA; const char* nB = has_next ? (const char*)g.Bt + (size_t)nxt.pn * tstep : cB;
;     ...
; #pragma unroll
;         for (int a = 0; a < 2; ++a)
; #pragma unroll
;             for (int b = 0; b < 2; ++b)
; #pragma unroll
;                 for (int m = 0; m < 4; ++m)
; #pragma unroll
;                     for (int n = 0; n < 2; ++n) acc[a][b][m][n] = (f32x4){0.f, 0.f, 0.f, 0.f};
.LBB0_885:
	s_ashr_i32 s31, s30, 31
	s_lshl_b64 s[36:37], s[30:31], 19
	s_add_u32 s36, s44, s36
	s_addc_u32 s37, s45, s37
	s_and_b64 s[38:39], s[0:1], exec
	s_cselect_b32 s31, s37, s43
	s_cselect_b32 s65, s36, s42
	s_ashr_i32 s29, s28, 31
	s_lshl_b64 s[38:39], s[28:29], 19
	s_add_u32 s38, s8, s38
	s_addc_u32 s39, s9, s39
	s_and_b64 s[48:49], s[0:1], exec
	s_cselect_b32 s29, s39, s47
	s_cselect_b32 s66, s38, s46
	s_add_u32 s42, s42, 0x40080
	s_addc_u32 s43, s43, 0
	s_add_u32 s67, s46, 0x100
	v_mov_b32_e32 v0, 0
	s_addc_u32 s72, s47, 0
	s_mov_b32 s73, -2
	v_mov_b64_e32 v[0:1], 0
	v_mov_b64_e32 v[2:3], 0
	v_mov_b64_e32 v[4:5], 0
	v_mov_b64_e32 v[6:7], 0
	v_mov_b64_e32 v[8:9], 0
	v_mov_b64_e32 v[10:11], 0
	v_mov_b64_e32 v[12:13], 0
	v_mov_b64_e32 v[14:15], 0
	v_mov_b64_e32 v[16:17], 0
	v_mov_b64_e32 v[18:19], 0
	v_mov_b64_e32 v[20:21], 0
	v_mov_b64_e32 v[22:23], 0
	v_mov_b64_e32 v[24:25], 0
	v_mov_b64_e32 v[26:27], 0
	v_mov_b64_e32 v[28:29], 0
	v_mov_b64_e32 v[30:31], 0
	v_mov_b64_e32 v[32:33], 0
	v_mov_b64_e32 v[34:35], 0
	v_mov_b64_e32 v[36:37], 0
	v_mov_b64_e32 v[38:39], 0
	v_mov_b64_e32 v[40:41], 0
	v_mov_b64_e32 v[42:43], 0
	v_mov_b64_e32 v[44:45], 0
	v_mov_b64_e32 v[46:47], 0
	v_mov_b64_e32 v[48:49], 0
	v_mov_b64_e32 v[50:51], 0
	v_mov_b64_e32 v[52:53], 0
	v_mov_b64_e32 v[54:55], 0
	v_mov_b64_e32 v[56:57], 0
	v_mov_b64_e32 v[58:59], 0
	v_mov_b64_e32 v[60:61], 0
	v_mov_b64_e32 v[62:63], 0
	v_mov_b64_e32 v[64:65], 0
	v_mov_b64_e32 v[66:67], 0
	v_mov_b64_e32 v[68:69], 0
	v_mov_b64_e32 v[70:71], 0
	v_mov_b64_e32 v[72:73], 0
	v_mov_b64_e32 v[74:75], 0
	v_mov_b64_e32 v[76:77], 0
	v_mov_b64_e32 v[78:79], 0
	v_mov_b64_e32 v[80:81], 0
	v_mov_b64_e32 v[82:83], 0
	v_mov_b64_e32 v[84:85], 0
	v_mov_b64_e32 v[86:87], 0
	v_mov_b64_e32 v[88:89], 0
	v_mov_b64_e32 v[90:91], 0
	v_mov_b64_e32 v[92:93], 0
	v_mov_b64_e32 v[94:95], 0
	v_mov_b64_e32 v[96:97], 0
	v_mov_b64_e32 v[98:99], 0
	v_mov_b64_e32 v[100:101], 0
	v_mov_b64_e32 v[102:103], 0
	v_mov_b64_e32 v[104:105], 0
	v_mov_b64_e32 v[106:107], 0
	v_mov_b64_e32 v[108:109], 0
	v_mov_b64_e32 v[110:111], 0
	v_mov_b64_e32 v[112:113], 0
	v_mov_b64_e32 v[114:115], 0
	v_mov_b64_e32 v[116:117], 0
	v_mov_b64_e32 v[118:119], 0
	v_mov_b64_e32 v[120:121], 0
	v_mov_b64_e32 v[122:123], 0
	v_mov_b64_e32 v[124:125], 0
	v_mov_b64_e32 v[126:127], 0
	s_branch .LBB0_886

; #define PG8_STAGE(bufoff, gbase, voff) do { _Pragma("unroll") for (int _i = 0; _i < 2; ++_i) \
;         __builtin_amdgcn_global_load_lds((const unsigned*)((const char*)(gbase) + (voff)[_i]), (PG8_LAS unsigned*)(lds + (bufoff) + ldsw + _i * 8192), 16, 0, 0); } while (0)
; #define PG8_LDA(dst, b, h) do { _Pragma("unroll") for (int m = 0; m < 4; ++m) _Pragma("unroll") for (int k = 0; k < 2; ++k) dst[m][k] = *(const PG8_LAS bf16x8*)(lds + PG8_SA(b, h) + aoff + m * 2048 + k * 1024); } while (0)
; #define PG8_LDB(dst, b, h) do { _Pragma("unroll") for (int n = 0; n < 2; ++n) _Pragma("unroll") for (int k = 0; k < 2; ++k) dst[n][k] = *(const PG8_LAS bf16x8*)(lds + PG8_SB(b, h) + boff + n * 2048 + k * 1024); } while (0)
; #define PG8_MMA(ai, bj, At, Bt) do { __builtin_amdgcn_s_setprio(1); _Pragma("unroll") for (int m = 0; m < 4; ++m) _Pragma("unroll") for (int n = 0; n < 2; ++n) _Pragma("unroll") for (int k = 0; k < 2; ++k) \
;         acc[ai][bj][m][n] = __builtin_amdgcn_mfma_f32_16x16x32_bf16(Bt[n][k], At[m][k], acc[ai][bj][m][n], 0, 0, 0); __builtin_amdgcn_s_setprio(0); } while (0)
; #define PG8_WAIT_V(n) asm volatile("s_waitcnt vmcnt(" #n ")" ::: "memory")
; #define PG8_WAIT_L(n) asm volatile("s_waitcnt lgkmcnt(" #n ")" ::: "memory")
; #define PG8_BAR __builtin_amdgcn_s_barrier()
; #define PG8_SCHED __builtin_amdgcn_sched_barrier(0)
; template <class Epi, class Sched, bool ALIGN_EPI = false, bool SP2 = false, bool AROWS128 = false>
; __device__ __forceinline__ void gemm_phase(PG8_LAS unsigned char* lds, const Gemm g, const Sched& S, const Epi& E) {
;     ...
;             PG8_LDB(B0, 0, 0); PG8_LDB(B1, 0, 1); PG8_SCHED; PG8_LDA(At, 0, 0); PG8_STAGE(PG8_SA(1, 1), a1 + hstepA, voffA);
;             PG8_WAIT_V(8); PG8_WAIT_L(0); PG8_BAR; PG8_MMA(0, 0, At, B0); PG8_MMA(0, 1, At, B1); PG8_BAR; PG8_SCHED;
;             PG8_LDA(At, 0, 1); PG8_STAGE(PG8_SB(0, 0), b2, voffB); PG8_STAGE(PG8_SB(0, 1), b2 + hstep, voffB); PG8_STAGE(PG8_SA(0, 0), a2, voffA);
;             PG8_WAIT_V(8); PG8_WAIT_L(0); PG8_BAR; PG8_MMA(1, 0, At, B0); PG8_MMA(1, 1, At, B1); PG8_BAR; PG8_SCHED;
;             PG8_LDB(B0, 1, 0); PG8_LDB(B1, 1, 1); PG8_SCHED; PG8_LDA(At, 1, 0); PG8_STAGE(PG8_SA(0, 1), a2 + hstepA, voffA);
;             PG8_WAIT_V(8); PG8_WAIT_L(0); PG8_BAR; PG8_MMA(0, 0, At, B0); PG8_MMA(0, 1, At, B1); PG8_BAR; PG8_SCHED;
.LBB0_886:
	ds_read_b128 v[152:155], v149
	ds_read_b128 v[156:159], v149 offset:1024
	ds_read_b128 v[160:163], v149 offset:2048
	ds_read_b128 v[164:167], v149 offset:3072
	ds_read_b128 v[168:171], v150
	ds_read_b128 v[172:175], v150 offset:1024
	ds_read_b128 v[176:179], v150 offset:2048
	ds_read_b128 v[180:183], v150 offset:3072
	s_add_u32 s46, s42, 0xfffc0080
	s_addc_u32 s47, s43, -1
	s_cmp_eq_u32 s73, 12
	s_cselect_b32 s49, s31, s47
	s_cselect_b32 s48, s65, s46
	s_cselect_b32 s47, s29, s72
	s_cselect_b32 s46, s66, s67
	v_lshl_add_u64 v[144:145], s[42:43], 0, v[136:137]
	s_add_i32 m0, s41, 0xc000
	ds_read_b128 v[184:187], v151
	ds_read_b128 v[188:191], v151 offset:1024
	ds_read_b128 v[192:195], v151 offset:2048
	ds_read_b128 v[196:199], v151 offset:3072
	ds_read_b128 v[200:203], v151 offset:4096
	ds_read_b128 v[204:207], v151 offset:5120
	ds_read_b128 v[212:215], v151 offset:6144
	ds_read_b128 v[216:219], v151 offset:7168
	global_load_lds_dwordx4 v[144:145], off
	v_lshl_add_u64 v[144:145], s[42:43], 0, v[138:139]
	s_add_i32 m0, s41, 0xe000
	s_nop 0
	global_load_lds_dwordx4 v[144:145], off
	s_waitcnt vmcnt(8)
	s_waitcnt lgkmcnt(0)
	s_barrier
	s_setprio 1
	s_waitcnt lgkmcnt(0)
	v_mfma_f32_16x16x32_bf16 v[124:127], v[152:155], v[184:187], v[124:127]
	v_mfma_f32_16x16x32_bf16 v[120:123], v[160:163], v[184:187], v[120:123]
	v_mfma_f32_16x16x32_bf16 v[116:119], v[152:155], v[192:195], v[116:119]
	v_mfma_f32_16x16x32_bf16 v[108:111], v[160:163], v[192:195], v[108:111]
	v_mfma_f32_16x16x32_bf16 v[100:103], v[152:155], v[200:203], v[100:103]
	v_mfma_f32_16x16x32_bf16 v[92:95], v[160:163], v[200:203], v[92:95]
	v_mfma_f32_16x16x32_bf16 v[84:87], v[152:155], v[212:215], v[84:87]
	v_mfma_f32_16x16x32_bf16 v[76:79], v[160:163], v[212:215], v[76:79]
	v_mfma_f32_16x16x32_bf16 v[124:127], v[156:159], v[188:191], v[124:127]
	v_mfma_f32_16x16x32_bf16 v[120:123], v[164:167], v[188:191], v[120:123]
	v_mfma_f32_16x16x32_bf16 v[116:119], v[156:159], v[196:199], v[116:119]
	v_mfma_f32_16x16x32_bf16 v[108:111], v[164:167], v[196:199], v[108:111]
	v_mfma_f32_16x16x32_bf16 v[100:103], v[156:159], v[204:207], v[100:103]
	v_mfma_f32_16x16x32_bf16 v[92:95], v[164:167], v[204:207], v[92:95]
	v_mfma_f32_16x16x32_bf16 v[84:87], v[156:159], v[216:219], v[84:87]
	v_mfma_f32_16x16x32_bf16 v[76:79], v[164:167], v[216:219], v[76:79]
	s_setprio 0
	s_setprio 1
	v_mfma_f32_16x16x32_bf16 v[112:115], v[168:171], v[184:187], v[112:115]
	v_mfma_f32_16x16x32_bf16 v[104:107], v[176:179], v[184:187], v[104:107]
	v_mfma_f32_16x16x32_bf16 v[96:99], v[168:171], v[192:195], v[96:99]
	v_mfma_f32_16x16x32_bf16 v[88:91], v[176:179], v[192:195], v[88:91]
	v_mfma_f32_16x16x32_bf16 v[80:83], v[168:171], v[200:203], v[80:83]
	v_mfma_f32_16x16x32_bf16 v[72:75], v[176:179], v[200:203], v[72:75]
	v_mfma_f32_16x16x32_bf16 v[68:71], v[168:171], v[212:215], v[68:71]
	v_mfma_f32_16x16x32_bf16 v[64:67], v[176:179], v[212:215], v[64:67]
	v_mfma_f32_16x16x32_bf16 v[112:115], v[172:175], v[188:191], v[112:115]
	v_mfma_f32_16x16x32_bf16 v[104:107], v[180:183], v[188:191], v[104:107]
	v_mfma_f32_16x16x32_bf16 v[96:99], v[172:175], v[196:199], v[96:99]
	v_mfma_f32_16x16x32_bf16 v[88:91], v[180:183], v[196:199], v[88:91]
	v_mfma_f32_16x16x32_bf16 v[80:83], v[172:175], v[204:207], v[80:83]
	v_mfma_f32_16x16x32_bf16 v[72:75], v[180:183], v[204:207], v[72:75]
	v_mfma_f32_16x16x32_bf16 v[68:71], v[172:175], v[216:219], v[68:71]
	v_mfma_f32_16x16x32_bf16 v[64:67], v[180:183], v[216:219], v[64:67]
	s_setprio 0
	s_barrier
	s_add_i32 s76, s58, s3
	v_lshl_add_u64 v[144:145], s[46:47], 0, v[132:133]
	s_mov_b32 m0, s76
	ds_read_b128 v[184:187], v151 offset:16384
	ds_read_b128 v[188:191], v151 offset:17408
	ds_read_b128 v[192:195], v151 offset:18432
	ds_read_b128 v[196:199], v151 offset:19456
	ds_read_b128 v[200:203], v151 offset:20480
	ds_read_b128 v[204:207], v151 offset:21504
	ds_read_b128 v[212:215], v151 offset:22528
	ds_read_b128 v[216:219], v151 offset:23552
	global_load_lds_dwordx4 v[144:145], off
	s_add_i32 m0, s76, 0x2000
	s_add_u32 s76, s46, 0x40000
	v_lshl_add_u64 v[208:209], s[46:47], 0, v[128:129]
	s_addc_u32 s77, s47, 0
	s_add_i32 s78, s59, s3
	global_load_lds_dwordx4 v[208:209], off
	v_lshl_add_u64 v[220:221], s[76:77], 0, v[132:133]
	s_mov_b32 m0, s78
	v_lshl_add_u64 v[222:223], s[48:49], 0, v[130:131]
	global_load_lds_dwordx4 v[220:221], off
	v_lshl_add_u64 v[220:221], s[76:77], 0, v[128:129]
	s_add_i32 m0, s78, 0x2000
	s_nop 0
	global_load_lds_dwordx4 v[220:221], off
	v_lshl_add_u64 v[220:221], s[48:49], 0, v[134:135]
	s_mov_b32 m0, s41
	s_nop 0
	global_load_lds_dwordx4 v[220:221], off
	s_mov_b32 m0, s50
	s_nop 0
	global_load_lds_dwordx4 v[222:223], off
	s_waitcnt vmcnt(8)
	s_waitcnt lgkmcnt(0)
	s_barrier
; #define PG8_STAGE(bufoff, gbase, voff) do { _Pragma("unroll") for (int _i = 0; _i < 2; ++_i) \
;         __builtin_amdgcn_global_load_lds((const unsigned*)((const char*)(gbase) + (voff)[_i]), (PG8_LAS unsigned*)(lds + (bufoff) + ldsw + _i * 8192), 16, 0, 0); } while (0)
; #define PG8_LDA(dst, b, h) do { _Pragma("unroll") for (int m = 0; m < 4; ++m) _Pragma("unroll") for (int k = 0; k < 2; ++k) dst[m][k] = *(const PG8_LAS bf16x8*)(lds + PG8_SA(b, h) + aoff + m * 2048 + k * 1024); } while (0)
; #define PG8_LDB(dst, b, h) do { _Pragma("unroll") for (int n = 0; n < 2; ++n) _Pragma("unroll") for (int k = 0; k < 2; ++k) dst[n][k] = *(const PG8_LAS bf16x8*)(lds + PG8_SB(b, h) + boff + n * 2048 + k * 1024); } while (0)
; #define PG8_MMA(ai, bj, At, Bt) do { __builtin_amdgcn_s_setprio(1); _Pragma("unroll") for (int m = 0; m < 4; ++m) _Pragma("unroll") for (int n = 0; n < 2; ++n) _Pragma("unroll") for (int k = 0; k < 2; ++k) \
;         acc[ai][bj][m][n] = __builtin_amdgcn_mfma_f32_16x16x32_bf16(Bt[n][k], At[m][k], acc[ai][bj][m][n], 0, 0, 0); __builtin_amdgcn_s_setprio(0); } while (0)
; #define PG8_WAIT_V(n) asm volatile("s_waitcnt vmcnt(" #n ")" ::: "memory")
; #define PG8_WAIT_L(n) asm volatile("s_waitcnt lgkmcnt(" #n ")" ::: "memory")
; #define PG8_BAR __builtin_amdgcn_s_barrier()
; #define PG8_SCHED __builtin_amdgcn_sched_barrier(0)
; template <class Epi, class Sched, bool ALIGN_EPI = false, bool SP2 = false, bool AROWS128 = false>
; __device__ __forceinline__ void gemm_phase(PG8_LAS unsigned char* lds, const Gemm g, const Sched& S, const Epi& E) {
;     ...
;             PG8_WAIT_V(8); PG8_WAIT_L(0); PG8_BAR; PG8_MMA(1, 0, At, B0); PG8_MMA(1, 1, At, B1); PG8_BAR; PG8_SCHED;
;             PG8_LDB(B0, 1, 0); PG8_LDB(B1, 1, 1); PG8_SCHED; PG8_LDA(At, 1, 0); PG8_STAGE(PG8_SA(0, 1), a2 + hstepA, voffA);
;             PG8_WAIT_V(8); PG8_WAIT_L(0); PG8_BAR; PG8_MMA(0, 0, At, B0); PG8_MMA(0, 1, At, B1); PG8_BAR; PG8_SCHED;
	s_setprio 1
	s_waitcnt lgkmcnt(0)
	v_mfma_f32_16x16x32_bf16 v[60:63], v[152:155], v[184:187], v[60:63]
	v_mfma_f32_16x16x32_bf16 v[56:59], v[160:163], v[184:187], v[56:59]
	v_mfma_f32_16x16x32_bf16 v[52:55], v[152:155], v[192:195], v[52:55]
	v_mfma_f32_16x16x32_bf16 v[44:47], v[160:163], v[192:195], v[44:47]
	v_mfma_f32_16x16x32_bf16 v[36:39], v[152:155], v[200:203], v[36:39]
	v_mfma_f32_16x16x32_bf16 v[28:31], v[160:163], v[200:203], v[28:31]
	v_mfma_f32_16x16x32_bf16 v[20:23], v[152:155], v[212:215], v[20:23]
	v_mfma_f32_16x16x32_bf16 v[12:15], v[160:163], v[212:215], v[12:15]
	v_mfma_f32_16x16x32_bf16 v[60:63], v[156:159], v[188:191], v[60:63]
	v_mfma_f32_16x16x32_bf16 v[56:59], v[164:167], v[188:191], v[56:59]
	v_mfma_f32_16x16x32_bf16 v[52:55], v[156:159], v[196:199], v[52:55]
	v_mfma_f32_16x16x32_bf16 v[44:47], v[164:167], v[196:199], v[44:47]
	v_mfma_f32_16x16x32_bf16 v[36:39], v[156:159], v[204:207], v[36:39]
	v_mfma_f32_16x16x32_bf16 v[28:31], v[164:167], v[204:207], v[28:31]
	v_mfma_f32_16x16x32_bf16 v[20:23], v[156:159], v[216:219], v[20:23]
	v_mfma_f32_16x16x32_bf16 v[12:15], v[164:167], v[216:219], v[12:15]
	s_setprio 0
	s_setprio 1
	v_mfma_f32_16x16x32_bf16 v[48:51], v[168:171], v[184:187], v[48:51]
	v_mfma_f32_16x16x32_bf16 v[40:43], v[176:179], v[184:187], v[40:43]
	v_mfma_f32_16x16x32_bf16 v[32:35], v[168:171], v[192:195], v[32:35]
	v_mfma_f32_16x16x32_bf16 v[24:27], v[176:179], v[192:195], v[24:27]
	v_mfma_f32_16x16x32_bf16 v[16:19], v[168:171], v[200:203], v[16:19]
	v_mfma_f32_16x16x32_bf16 v[8:11], v[176:179], v[200:203], v[8:11]
	v_mfma_f32_16x16x32_bf16 v[4:7], v[168:171], v[212:215], v[4:7]
	v_mfma_f32_16x16x32_bf16 v[0:3], v[176:179], v[212:215], v[0:3]
	v_mfma_f32_16x16x32_bf16 v[48:51], v[172:175], v[188:191], v[48:51]
	v_mfma_f32_16x16x32_bf16 v[40:43], v[180:183], v[188:191], v[40:43]
	v_mfma_f32_16x16x32_bf16 v[32:35], v[172:175], v[196:199], v[32:35]
	v_mfma_f32_16x16x32_bf16 v[24:27], v[180:183], v[196:199], v[24:27]
	v_mfma_f32_16x16x32_bf16 v[16:19], v[172:175], v[204:207], v[16:19]
	v_mfma_f32_16x16x32_bf16 v[8:11], v[180:183], v[204:207], v[8:11]
	v_mfma_f32_16x16x32_bf16 v[4:7], v[172:175], v[216:219], v[4:7]
	v_mfma_f32_16x16x32_bf16 v[0:3], v[180:183], v[216:219], v[0:3]
	s_setprio 0
	s_barrier
	s_add_i32 s76, 0, 0x18000
	s_add_i32 s77, 0, 0x1c000
	v_add_u32_e32 v164, s76, v147
	v_add_u32_e32 v180, s77, v147
	ds_read_b128 v[152:155], v164
	ds_read_b128 v[156:159], v164 offset:1024
	ds_read_b128 v[160:163], v164 offset:2048
	ds_read_b128 v[164:167], v164 offset:3072
	ds_read_b128 v[168:171], v180
	ds_read_b128 v[172:175], v180 offset:1024
	ds_read_b128 v[176:179], v180 offset:2048
	ds_read_b128 v[180:183], v180 offset:3072
	s_add_u32 s48, s48, 0x40000
	s_addc_u32 s49, s49, 0
	s_mov_b32 m0, s51
	v_lshl_add_u64 v[224:225], s[48:49], 0, v[134:135]
	ds_read_b128 v[184:187], v151 offset:32768
	ds_read_b128 v[188:191], v151 offset:33792
	ds_read_b128 v[192:195], v151 offset:34816
	ds_read_b128 v[196:199], v151 offset:35840
	ds_read_b128 v[200:203], v151 offset:36864
	ds_read_b128 v[204:207], v151 offset:37888
	ds_read_b128 v[212:215], v151 offset:38912
	ds_read_b128 v[216:219], v151 offset:39936
	global_load_lds_dwordx4 v[224:225], off
	v_lshl_add_u64 v[224:225], s[48:49], 0, v[130:131]
	s_mov_b32 m0, s52
	s_nop 0
	global_load_lds_dwordx4 v[224:225], off
	s_waitcnt vmcnt(8)
	s_waitcnt lgkmcnt(0)
	s_barrier
	s_setprio 1
	s_waitcnt lgkmcnt(0)
	v_mfma_f32_16x16x32_bf16 v[124:127], v[152:155], v[184:187], v[124:127]
	v_mfma_f32_16x16x32_bf16 v[120:123], v[160:163], v[184:187], v[120:123]
	v_mfma_f32_16x16x32_bf16 v[116:119], v[152:155], v[192:195], v[116:119]
	v_mfma_f32_16x16x32_bf16 v[108:111], v[160:163], v[192:195], v[108:111]
	v_mfma_f32_16x16x32_bf16 v[100:103], v[152:155], v[200:203], v[100:103]
	v_mfma_f32_16x16x32_bf16 v[92:95], v[160:163], v[200:203], v[92:95]
	v_mfma_f32_16x16x32_bf16 v[84:87], v[152:155], v[212:215], v[84:87]
	v_mfma_f32_16x16x32_bf16 v[76:79], v[160:163], v[212:215], v[76:79]
	v_mfma_f32_16x16x32_bf16 v[124:127], v[156:159], v[188:191], v[124:127]
	v_mfma_f32_16x16x32_bf16 v[120:123], v[164:167], v[188:191], v[120:123]
	v_mfma_f32_16x16x32_bf16 v[116:119], v[156:159], v[196:199], v[116:119]
	v_mfma_f32_16x16x32_bf16 v[108:111], v[164:167], v[196:199], v[108:111]
	v_mfma_f32_16x16x32_bf16 v[100:103], v[156:159], v[204:207], v[100:103]
	v_mfma_f32_16x16x32_bf16 v[92:95], v[164:167], v[204:207], v[92:95]
	v_mfma_f32_16x16x32_bf16 v[84:87], v[156:159], v[216:219], v[84:87]
	v_mfma_f32_16x16x32_bf16 v[76:79], v[164:167], v[216:219], v[76:79]
	s_setprio 0
	s_setprio 1
	v_mfma_f32_16x16x32_bf16 v[112:115], v[168:171], v[184:187], v[112:115]
	v_mfma_f32_16x16x32_bf16 v[104:107], v[176:179], v[184:187], v[104:107]
	v_mfma_f32_16x16x32_bf16 v[96:99], v[168:171], v[192:195], v[96:99]
	v_mfma_f32_16x16x32_bf16 v[88:91], v[176:179], v[192:195], v[88:91]
	v_mfma_f32_16x16x32_bf16 v[80:83], v[168:171], v[200:203], v[80:83]
	v_mfma_f32_16x16x32_bf16 v[72:75], v[176:179], v[200:203], v[72:75]
	v_mfma_f32_16x16x32_bf16 v[68:71], v[168:171], v[212:215], v[68:71]
	v_mfma_f32_16x16x32_bf16 v[64:67], v[176:179], v[212:215], v[64:67]
	v_mfma_f32_16x16x32_bf16 v[112:115], v[172:175], v[188:191], v[112:115]
	v_mfma_f32_16x16x32_bf16 v[104:107], v[180:183], v[188:191], v[104:107]
	v_mfma_f32_16x16x32_bf16 v[96:99], v[172:175], v[196:199], v[96:99]
	v_mfma_f32_16x16x32_bf16 v[88:91], v[180:183], v[196:199], v[88:91]
	v_mfma_f32_16x16x32_bf16 v[80:83], v[172:175], v[204:207], v[80:83]
	v_mfma_f32_16x16x32_bf16 v[72:75], v[180:183], v[204:207], v[72:75]
	v_mfma_f32_16x16x32_bf16 v[68:71], v[172:175], v[216:219], v[68:71]
	v_mfma_f32_16x16x32_bf16 v[64:67], v[180:183], v[216:219], v[64:67]
	s_setprio 0
	s_barrier
; #define PG8_STAGE(bufoff, gbase, voff) do { _Pragma("unroll") for (int _i = 0; _i < 2; ++_i) \
;         __builtin_amdgcn_global_load_lds((const unsigned*)((const char*)(gbase) + (voff)[_i]), (PG8_LAS unsigned*)(lds + (bufoff) + ldsw + _i * 8192), 16, 0, 0); } while (0)
; #define PG8_LDA(dst, b, h) do { _Pragma("unroll") for (int m = 0; m < 4; ++m) _Pragma("unroll") for (int k = 0; k < 2; ++k) dst[m][k] = *(const PG8_LAS bf16x8*)(lds + PG8_SA(b, h) + aoff + m * 2048 + k * 1024); } while (0)
; #define PG8_MMA(ai, bj, At, Bt) do { __builtin_amdgcn_s_setprio(1); _Pragma("unroll") for (int m = 0; m < 4; ++m) _Pragma("unroll") for (int n = 0; n < 2; ++n) _Pragma("unroll") for (int k = 0; k < 2; ++k) \
;         acc[ai][bj][m][n] = __builtin_amdgcn_mfma_f32_16x16x32_bf16(Bt[n][k], At[m][k], acc[ai][bj][m][n], 0, 0, 0); __builtin_amdgcn_s_setprio(0); } while (0)
; #define PG8_WAIT_V(n) asm volatile("s_waitcnt vmcnt(" #n ")" ::: "memory")
; #define PG8_WAIT_L(n) asm volatile("s_waitcnt lgkmcnt(" #n ")" ::: "memory")
; #define PG8_BAR __builtin_amdgcn_s_barrier()
; #define PG8_SCHED __builtin_amdgcn_sched_barrier(0)
; template <class Epi, class Sched, bool ALIGN_EPI = false, bool SP2 = false, bool AROWS128 = false>
; __device__ __forceinline__ void gemm_phase(PG8_LAS unsigned char* lds, const Gemm g, const Sched& S, const Epi& E) {
;     ...
;         for (int t = 0; t < nt; t += 2) {
;     ...
;             PG8_LDA(At, 1, 1); PG8_STAGE(PG8_SB(1, 0), b3, voffB); PG8_STAGE(PG8_SB(1, 1), b3 + hstep, voffB); PG8_STAGE(PG8_SA(1, 0), a3, voffA);
;             PG8_WAIT_V(8); PG8_WAIT_L(0); PG8_BAR; PG8_MMA(1, 0, At, B0); PG8_MMA(1, 1, At, B1); PG8_BAR; PG8_SCHED;
	s_add_i32 s48, s76, s3
	v_lshl_add_u64 v[144:145], v[144:145], 0, s[16:17]
	s_mov_b32 m0, s48
	ds_read_b128 v[184:187], v151 offset:49152
	ds_read_b128 v[188:191], v151 offset:50176
	ds_read_b128 v[192:195], v151 offset:51200
	ds_read_b128 v[196:199], v151 offset:52224
	ds_read_b128 v[200:203], v151 offset:53248
	ds_read_b128 v[204:207], v151 offset:54272
	ds_read_b128 v[212:215], v151 offset:55296
	ds_read_b128 v[216:219], v151 offset:56320
	global_load_lds_dwordx4 v[144:145], off
	s_add_i32 m0, s48, 0x2000
	s_add_u32 s46, s46, 0x40080
	v_lshl_add_u64 v[144:145], v[208:209], 0, s[16:17]
	s_addc_u32 s47, s47, 0
	s_add_i32 s48, s77, s3
	global_load_lds_dwordx4 v[144:145], off
	v_lshl_add_u64 v[144:145], s[46:47], 0, v[132:133]
	s_mov_b32 m0, s48
	s_nop 0
	global_load_lds_dwordx4 v[144:145], off
	v_lshl_add_u64 v[144:145], s[46:47], 0, v[128:129]
	s_add_i32 m0, s48, 0x2000
	s_nop 0
	global_load_lds_dwordx4 v[144:145], off
	v_lshl_add_u64 v[144:145], v[220:221], 0, s[16:17]
	s_mov_b32 m0, s54
	s_nop 0
	global_load_lds_dwordx4 v[144:145], off
	v_lshl_add_u64 v[144:145], v[222:223], 0, s[16:17]
	s_mov_b32 m0, s55
	s_nop 0
	global_load_lds_dwordx4 v[144:145], off
	s_waitcnt vmcnt(8)
	s_waitcnt lgkmcnt(0)
	s_barrier
	s_setprio 1
	s_waitcnt lgkmcnt(0)
	v_mfma_f32_16x16x32_bf16 v[60:63], v[152:155], v[184:187], v[60:63]
	v_mfma_f32_16x16x32_bf16 v[56:59], v[160:163], v[184:187], v[56:59]
	v_mfma_f32_16x16x32_bf16 v[52:55], v[152:155], v[192:195], v[52:55]
	v_mfma_f32_16x16x32_bf16 v[44:47], v[160:163], v[192:195], v[44:47]
	v_mfma_f32_16x16x32_bf16 v[36:39], v[152:155], v[200:203], v[36:39]
	v_mfma_f32_16x16x32_bf16 v[28:31], v[160:163], v[200:203], v[28:31]
	v_mfma_f32_16x16x32_bf16 v[20:23], v[152:155], v[212:215], v[20:23]
	v_mfma_f32_16x16x32_bf16 v[12:15], v[160:163], v[212:215], v[12:15]
	v_mfma_f32_16x16x32_bf16 v[60:63], v[156:159], v[188:191], v[60:63]
	v_mfma_f32_16x16x32_bf16 v[56:59], v[164:167], v[188:191], v[56:59]
	v_mfma_f32_16x16x32_bf16 v[52:55], v[156:159], v[196:199], v[52:55]
	v_mfma_f32_16x16x32_bf16 v[44:47], v[164:167], v[196:199], v[44:47]
	v_mfma_f32_16x16x32_bf16 v[36:39], v[156:159], v[204:207], v[36:39]
	v_mfma_f32_16x16x32_bf16 v[28:31], v[164:167], v[204:207], v[28:31]
	v_mfma_f32_16x16x32_bf16 v[20:23], v[156:159], v[216:219], v[20:23]
	v_mfma_f32_16x16x32_bf16 v[12:15], v[164:167], v[216:219], v[12:15]
	s_setprio 0
	s_setprio 1
	v_mfma_f32_16x16x32_bf16 v[48:51], v[168:171], v[184:187], v[48:51]
	v_mfma_f32_16x16x32_bf16 v[40:43], v[176:179], v[184:187], v[40:43]
	v_mfma_f32_16x16x32_bf16 v[32:35], v[168:171], v[192:195], v[32:35]
	v_mfma_f32_16x16x32_bf16 v[24:27], v[176:179], v[192:195], v[24:27]
	v_mfma_f32_16x16x32_bf16 v[16:19], v[168:171], v[200:203], v[16:19]
	v_mfma_f32_16x16x32_bf16 v[8:11], v[176:179], v[200:203], v[8:11]
	v_mfma_f32_16x16x32_bf16 v[4:7], v[168:171], v[212:215], v[4:7]
	v_mfma_f32_16x16x32_bf16 v[0:3], v[176:179], v[212:215], v[0:3]
	v_mfma_f32_16x16x32_bf16 v[48:51], v[172:175], v[188:191], v[48:51]
	v_mfma_f32_16x16x32_bf16 v[40:43], v[180:183], v[188:191], v[40:43]
	v_mfma_f32_16x16x32_bf16 v[32:35], v[172:175], v[196:199], v[32:35]
	v_mfma_f32_16x16x32_bf16 v[24:27], v[180:183], v[196:199], v[24:27]
	v_mfma_f32_16x16x32_bf16 v[16:19], v[172:175], v[204:207], v[16:19]
	v_mfma_f32_16x16x32_bf16 v[8:11], v[180:183], v[204:207], v[8:11]
	v_mfma_f32_16x16x32_bf16 v[4:7], v[172:175], v[216:219], v[4:7]
	v_mfma_f32_16x16x32_bf16 v[0:3], v[180:183], v[216:219], v[0:3]
	s_setprio 0
	s_add_i32 s73, s73, 2
	s_add_u32 s42, s42, 0x100
	s_addc_u32 s43, s43, 0
	s_add_u32 s67, s67, 0x100
	s_addc_u32 s72, s72, 0
	s_cmp_gt_u32 s73, 13
	s_cbranch_scc0 .Lrot_k4
	s_barrier
	s_and_b64 vcc, exec, s[18:19]
	s_cbranch_vccz .LBB0_889
	s_barrier
